# hyena order-1 output written channel-major (bf16, two 16B stores/thread) into the consumed YT row; new transposition phase in the unused even-layer slot k==3 converts to MIX[tok][c] with coalesced sto
# speedup vs baseline: 1.0264x; 1.0159x over previous
.LBB0_299:
	s_or_b64 exec, exec, s[16:17]
	v_mov_b32_e32 v206, v208
	s_waitcnt lgkmcnt(0)
	s_barrier
	s_xor_b64 s[16:17], s[18:19], -1
	v_and_b32_e32 v104, 0xff, v206
	v_lshlrev_b32_e32 v105, 4, v206
	v_and_or_b32 v104, v105, s93, v104
	v_ashrrev_i32_e32 v105, 4, v104
	v_lshlrev_b32_e32 v105, 3, v105
	v_lshlrev_b32_e32 v104, 3, v104
	v_add3_u32 v207, s35, v105, v104
	ds_read_b64 v[106:107], v207
	ds_read_b64 v[108:109], v207 offset:2176
	ds_read_b64 v[110:111], v207 offset:4352
	ds_read_b64 v[112:113], v207 offset:6528
	ds_read_b64 v[114:115], v207 offset:8704
	ds_read_b64 v[116:117], v207 offset:10880
	ds_read_b64 v[118:119], v207 offset:13056
	ds_read_b64 v[120:121], v207 offset:15232
	ds_read_b64 v[122:123], v207 offset:17408
	ds_read_b64 v[124:125], v207 offset:19584
	ds_read_b64 v[126:127], v207 offset:21760
	ds_read_b64 v[128:129], v207 offset:23936
	ds_read_b64 v[130:131], v207 offset:26112
	ds_read_b64 v[132:133], v207 offset:28288
	ds_read_b64 v[134:135], v207 offset:30464
	ds_read_b64 v[176:177], v207 offset:32640
	s_waitcnt lgkmcnt(5)
	v_pk_add_f32 v[184:185], v[110:111], v[126:127]
	v_pk_add_f32 v[110:111], v[110:111], v[126:127] neg_lo:[0,1] neg_hi:[0,1]
	s_waitcnt lgkmcnt(2)
	v_pk_add_f32 v[194:195], v[116:117], v[132:133]
	s_waitcnt lgkmcnt(1)
	v_pk_add_f32 v[186:187], v[118:119], v[134:135]
	v_pk_add_f32 v[118:119], v[118:119], v[134:135] neg_lo:[0,1] neg_hi:[0,1]
	v_pk_add_f32 v[116:117], v[116:117], v[132:133] neg_lo:[0,1] neg_hi:[0,1]
	v_xor_b32_e32 v127, 0x80000000, v118
	v_mov_b32_e32 v126, v119
	v_pk_add_f32 v[192:193], v[108:109], v[124:125]
	v_pk_add_f32 v[118:119], v[110:111], v[126:127]
	v_pk_add_f32 v[108:109], v[108:109], v[124:125] neg_lo:[0,1] neg_hi:[0,1]
	v_xor_b32_e32 v125, 0x80000000, v116
	v_mov_b32_e32 v124, v117
	v_pk_add_f32 v[180:181], v[114:115], v[130:131]
	v_pk_add_f32 v[114:115], v[114:115], v[130:131] neg_lo:[0,1] neg_hi:[0,1]
	v_pk_mul_f32 v[130:131], v[118:119], s[24:25] op_sel_hi:[1,0]
	v_pk_add_f32 v[116:117], v[108:109], v[124:125]
	v_pk_fma_f32 v[134:135], v[118:119], s[24:25], v[130:131] op_sel:[0,0,1] op_sel_hi:[1,0,0]
	v_pk_fma_f32 v[118:119], v[118:119], s[24:25], v[130:131] op_sel_hi:[1,0,0] neg_lo:[0,0,1] neg_hi:[0,0,1]
	v_pk_mul_f32 v[130:131], v[116:117], s[30:31] op_sel_hi:[1,0]
	v_pk_add_f32 v[178:179], v[106:107], v[122:123]
	v_pk_fma_f32 v[132:133], v[116:117], s[22:23], v[130:131] op_sel:[0,0,1] op_sel_hi:[1,0,0]
	v_pk_fma_f32 v[116:117], v[116:117], s[22:23], v[130:131] op_sel:[0,0,1] op_sel_hi:[1,0,0] neg_lo:[0,0,1] neg_hi:[0,0,1]
	v_pk_add_f32 v[182:183], v[178:179], v[180:181]
	v_pk_add_f32 v[188:189], v[184:185], v[186:187]
	s_waitcnt lgkmcnt(0)
	v_pk_add_f32 v[200:201], v[120:121], v[176:177]
	v_mov_b32_e32 v133, v117
	v_pk_add_f32 v[116:117], v[120:121], v[176:177] neg_lo:[0,1] neg_hi:[0,1]
	v_pk_add_f32 v[176:177], v[178:179], v[180:181] neg_lo:[0,1] neg_hi:[0,1]
	v_pk_add_f32 v[178:179], v[184:185], v[186:187] neg_lo:[0,1] neg_hi:[0,1]
	v_pk_add_f32 v[184:185], v[192:193], v[194:195] neg_lo:[0,1] neg_hi:[0,1]
	v_pk_add_f32 v[198:199], v[112:113], v[128:129]
	v_pk_add_f32 v[112:113], v[112:113], v[128:129] neg_lo:[0,1] neg_hi:[0,1]
	v_xor_b32_e32 v121, 0x80000000, v116
	v_mov_b32_e32 v120, v117
	v_pk_mul_f32 v[186:187], v[184:185], s[24:25] op_sel_hi:[1,0]
	v_pk_add_f32 v[196:197], v[192:193], v[194:195]
	v_pk_add_f32 v[116:117], v[112:113], v[120:121]
	v_pk_fma_f32 v[192:193], v[184:185], s[24:25], v[186:187] op_sel:[0,0,1] op_sel_hi:[1,0,0]
	v_pk_fma_f32 v[184:185], v[184:185], s[24:25], v[186:187] op_sel_hi:[1,0,0] neg_lo:[0,0,1] neg_hi:[0,0,1]
	v_pk_mul_f32 v[128:129], v[116:117], s[22:23] op_sel_hi:[1,0]
	v_mov_b32_e32 v193, v185
	v_pk_add_f32 v[184:185], v[198:199], v[200:201] neg_lo:[0,1] neg_hi:[0,1]
	v_pk_fma_f32 v[130:131], v[116:117], s[30:31], v[128:129] op_sel:[0,0,1] op_sel_hi:[1,0,0]
	v_pk_fma_f32 v[116:117], v[116:117], s[30:31], v[128:129] op_sel:[0,0,1] op_sel_hi:[1,0,0] neg_lo:[0,0,1] neg_hi:[0,0,1]
	v_mul_f32_e32 v186, 0x3f3504f3, v184
	v_pk_add_f32 v[106:107], v[106:107], v[122:123] neg_lo:[0,1] neg_hi:[0,1]
	v_xor_b32_e32 v123, 0x80000000, v114
	v_mov_b32_e32 v122, v115
	v_mov_b32_e32 v131, v117
	v_pk_fma_f32 v[184:185], v[184:185], s[24:25], v[186:187] op_sel:[1,0,0] op_sel_hi:[1,1,0] neg_lo:[0,0,1] neg_hi:[0,0,1]
	v_pk_add_f32 v[108:109], v[108:109], v[124:125] neg_lo:[0,1] neg_hi:[0,1]
	v_pk_add_f32 v[114:115], v[106:107], v[122:123]
	v_mov_b32_e32 v135, v119
	v_pk_add_f32 v[116:117], v[132:133], v[130:131] neg_lo:[0,1] neg_hi:[0,1]
	v_xor_b32_e32 v181, 0x80000000, v178
	v_mov_b32_e32 v180, v179
	v_pk_add_f32 v[186:187], v[192:193], v[184:185] neg_lo:[0,1] neg_hi:[0,1]
	v_pk_mul_f32 v[124:125], v[108:109], s[22:23] op_sel_hi:[1,0]
	v_pk_add_f32 v[118:119], v[114:115], v[134:135] neg_lo:[0,1] neg_hi:[0,1]
	v_xor_b32_e32 v129, 0x80000000, v116
	v_mov_b32_e32 v128, v117
	v_pk_add_f32 v[178:179], v[176:177], v[180:181] neg_lo:[0,1] neg_hi:[0,1]
	v_xor_b32_e32 v195, 0x80000000, v186
	v_mov_b32_e32 v194, v187
	v_pk_add_f32 v[110:111], v[110:111], v[126:127] neg_lo:[0,1] neg_hi:[0,1]
	v_pk_fma_f32 v[126:127], v[108:109], s[30:31], v[124:125] op_sel:[0,0,1] op_sel_hi:[1,0,0]
	v_pk_fma_f32 v[108:109], v[108:109], s[30:31], v[124:125] op_sel:[0,0,1] op_sel_hi:[1,0,0] neg_lo:[0,0,1] neg_hi:[0,0,1]
	v_pk_add_f32 v[116:117], v[118:119], v[128:129]
	v_pk_add_f32 v[186:187], v[178:179], v[194:195]
	v_mov_b32_e32 v127, v109
	v_pk_add_f32 v[108:109], v[112:113], v[120:121] neg_lo:[0,1] neg_hi:[0,1]
	v_pk_add_f32 v[118:119], v[118:119], v[128:129] neg_lo:[0,1] neg_hi:[0,1]
	v_pk_add_f32 v[128:129], v[178:179], v[194:195] neg_lo:[0,1] neg_hi:[0,1]
	v_cvt_f32_ubyte0_e32 v178, v206
	v_pk_mul_f32 v[112:113], v[108:109], s[30:31]
	v_pk_add_f32 v[114:115], v[114:115], v[134:135]
	v_pk_add_f32 v[134:135], v[176:177], v[180:181]
	v_pk_add_f32 v[176:177], v[192:193], v[184:185]
	v_mul_f32_e32 v192, 0x39800000, v178
	v_pk_fma_f32 v[108:109], v[108:109], s[22:23], v[112:113] op_sel:[0,0,1] op_sel_hi:[1,0,0] neg_lo:[1,0,0] neg_hi:[1,0,0]
	v_sin_f32_e32 v178, v192
	v_pk_add_f32 v[190:191], v[182:183], v[188:189]
	v_pk_add_f32 v[106:107], v[106:107], v[122:123] neg_lo:[0,1] neg_hi:[0,1]
	v_mul_f32_e32 v122, 0x3f3504f3, v110
	v_pk_add_f32 v[112:113], v[126:127], v[108:109] neg_lo:[0,1] neg_hi:[0,1]
	v_pk_add_f32 v[108:109], v[126:127], v[108:109]
	v_pk_add_f32 v[126:127], v[182:183], v[188:189] neg_lo:[0,1] neg_hi:[0,1]
	v_cos_f32_e32 v188, v192
	v_pk_fma_f32 v[110:111], v[110:111], s[24:25], v[122:123] op_sel:[1,0,0] op_sel_hi:[1,1,0] neg_lo:[0,0,1] neg_hi:[0,0,1]
	v_pk_add_f32 v[130:131], v[132:133], v[130:131]
	v_pk_add_f32 v[122:123], v[106:107], v[110:111] neg_lo:[0,1] neg_hi:[0,1]
	v_xor_b32_e32 v121, 0x80000000, v112
	v_mov_b32_e32 v120, v113
	v_pk_add_f32 v[132:133], v[114:115], v[130:131] neg_lo:[0,1] neg_hi:[0,1]
	v_pk_add_f32 v[114:115], v[114:115], v[130:131]
	v_pk_add_f32 v[112:113], v[122:123], v[120:121]
	v_pk_add_f32 v[120:121], v[122:123], v[120:121] neg_lo:[0,1] neg_hi:[0,1]
	v_pk_mul_f32 v[122:123], v[178:179], v[114:115] op_sel:[0,1] op_sel_hi:[0,0]
	v_pk_fma_f32 v[130:131], v[188:189], v[114:115], v[122:123]
	v_pk_fma_f32 v[114:115], v[188:189], v[114:115], v[122:123] op_sel_hi:[0,1,1] neg_lo:[0,0,1] neg_hi:[0,0,1]
	v_mov_b32_e32 v189, v178
	v_pk_add_f32 v[180:181], v[134:135], v[176:177] neg_lo:[0,1] neg_hi:[0,1]
	v_mov_b32_e32 v131, v115
	v_pk_mul_f32 v[114:115], v[188:189], v[188:189]
	v_pk_add_f32 v[122:123], v[134:135], v[176:177]
	v_mul_f32_e32 v135, v188, v178
	v_mov_b32_e32 v134, v114
	v_mov_b32_e32 v114, v115
	v_mov_b32_e32 v115, v135
	v_pk_add_f32 v[202:203], v[198:199], v[200:201]
	v_pk_add_f32 v[176:177], v[134:135], v[114:115] neg_lo:[0,1] neg_hi:[0,1]
	v_pk_add_f32 v[114:115], v[134:135], v[114:115]
	v_pk_add_f32 v[204:205], v[196:197], v[202:203]
	v_pk_add_f32 v[106:107], v[106:107], v[110:111]
	v_mov_b32_e32 v134, v176
	v_mov_b32_e32 v135, v115
	v_pk_mul_f32 v[114:115], v[114:115], v[122:123] op_sel:[1,1] op_sel_hi:[1,0]
	v_mov_b32_e32 v179, v188
	v_pk_add_f32 v[104:105], v[190:191], v[204:205]
	v_pk_add_f32 v[124:125], v[190:191], v[204:205] neg_lo:[0,1] neg_hi:[0,1]
	v_pk_add_f32 v[110:111], v[106:107], v[108:109] neg_lo:[0,1] neg_hi:[0,1]
	v_pk_fma_f32 v[190:191], v[176:177], v[122:123], v[114:115]
	v_pk_fma_f32 v[114:115], v[176:177], v[122:123], v[114:115] op_sel_hi:[0,1,1] neg_lo:[0,0,1] neg_hi:[0,0,1]
	v_pk_add_f32 v[106:107], v[106:107], v[108:109]
	v_pk_mul_f32 v[108:109], v[178:179], v[134:135]
	v_mov_b32_e32 v191, v115
	v_pk_mul_f32 v[114:115], v[188:189], v[134:135]
	v_pk_add_f32 v[108:109], v[108:109], v[108:109] op_sel:[1,0] op_sel_hi:[1,0]
	v_pk_add_f32 v[114:115], v[114:115], v[114:115] op_sel:[0,1] op_sel_hi:[0,1] neg_lo:[0,1] neg_hi:[0,1]
	v_pk_mul_f32 v[108:109], v[108:109], v[106:107] op_sel:[0,1] op_sel_hi:[1,0]
	v_pk_add_f32 v[182:183], v[196:197], v[202:203] neg_lo:[0,1] neg_hi:[0,1]
	v_pk_fma_f32 v[122:123], v[114:115], v[106:107], v[108:109]
	v_pk_fma_f32 v[106:107], v[114:115], v[106:107], v[108:109] neg_lo:[0,0,1] neg_hi:[0,0,1]
	v_mul_f32_e32 v108, 4.0, v192
	v_sin_f32_e32 v106, v108
	v_cos_f32_e32 v108, v108
	v_xor_b32_e32 v185, 0x80000000, v182
	v_mov_b32_e32 v184, v183
	v_pk_add_f32 v[114:115], v[126:127], v[184:185]
	v_pk_add_f32 v[182:183], v[126:127], v[184:185] neg_lo:[0,1] neg_hi:[0,1]
	v_pk_mul_f32 v[126:127], v[106:107], v[114:115] op_sel:[0,1] op_sel_hi:[0,0]
	v_mov_b32_e32 v123, v107
	v_pk_fma_f32 v[134:135], v[108:109], v[114:115], v[126:127]
	v_pk_fma_f32 v[114:115], v[108:109], v[114:115], v[126:127] op_sel_hi:[0,1,1] neg_lo:[0,0,1] neg_hi:[0,0,1]
	v_mov_b32_e32 v109, v106
	v_mov_b32_e32 v107, v108
	v_mov_b32_e32 v135, v115
	v_pk_mul_f32 v[114:115], v[188:189], v[108:109]
	v_pk_mul_f32 v[106:107], v[188:189], v[106:107]
	v_mov_b32_e32 v108, v114
	v_mov_b32_e32 v109, v106
	v_mov_b32_e32 v106, v115
	v_pk_add_f32 v[114:115], v[108:109], v[106:107] neg_lo:[0,1] neg_hi:[0,1]
	v_pk_add_f32 v[106:107], v[108:109], v[106:107]
	v_mov_b32_e32 v108, v114
	v_mov_b32_e32 v109, v107
	v_pk_mul_f32 v[106:107], v[106:107], v[116:117] op_sel:[1,1] op_sel_hi:[1,0]
	s_mov_b32 s18, s25
	v_pk_fma_f32 v[126:127], v[114:115], v[116:117], v[106:107]
	v_pk_fma_f32 v[106:107], v[114:115], v[116:117], v[106:107] op_sel_hi:[0,1,1] neg_lo:[0,0,1] neg_hi:[0,0,1]
	v_mov_b32_e32 v127, v107
	v_pk_mul_f32 v[106:107], v[188:189], v[108:109]
	v_pk_mul_f32 v[108:109], v[178:179], v[108:109]
	v_mov_b32_e32 v114, v106
	v_mov_b32_e32 v115, v109
	v_pk_mov_b32 v[106:107], v[106:107], v[108:109] op_sel:[1,0]
	s_mov_b32 s19, s24
	v_pk_add_f32 v[108:109], v[114:115], v[106:107] neg_lo:[0,1] neg_hi:[0,1]
	v_pk_add_f32 v[106:107], v[114:115], v[106:107]
	v_mov_b32_e32 v114, v108
	v_mov_b32_e32 v115, v107
	v_pk_mul_f32 v[106:107], v[106:107], v[186:187] op_sel:[1,1] op_sel_hi:[1,0]
	s_mov_b32 s88, s31
	v_pk_fma_f32 v[116:117], v[108:109], v[186:187], v[106:107]
	v_pk_fma_f32 v[106:107], v[108:109], v[186:187], v[106:107] op_sel_hi:[0,1,1] neg_lo:[0,0,1] neg_hi:[0,0,1]
	v_pk_mul_f32 v[108:109], v[178:179], v[114:115]
	v_mov_b32_e32 v117, v107
	v_pk_mul_f32 v[106:107], v[188:189], v[114:115]
	v_pk_add_f32 v[108:109], v[108:109], v[108:109] op_sel:[1,0] op_sel_hi:[1,0]
	v_pk_add_f32 v[106:107], v[106:107], v[106:107] op_sel:[0,1] op_sel_hi:[0,1] neg_lo:[0,1] neg_hi:[0,1]
	v_pk_mul_f32 v[108:109], v[108:109], v[112:113] op_sel:[0,1] op_sel_hi:[1,0]
	s_mov_b32 s89, s30
	v_pk_fma_f32 v[114:115], v[106:107], v[112:113], v[108:109]
	v_pk_fma_f32 v[106:107], v[106:107], v[112:113], v[108:109] neg_lo:[0,0,1] neg_hi:[0,0,1]
	v_mul_f32_e32 v115, 0x41000000, v192
	v_sin_f32_e32 v176, v115
	v_cos_f32_e32 v184, v115
	v_mov_b32_e32 v115, v107
	v_pk_mul_f32 v[106:107], v[176:177], v[124:125] op_sel:[0,1] op_sel_hi:[0,0]
	v_pk_fma_f32 v[108:109], v[184:185], v[124:125], v[106:107]
	v_pk_fma_f32 v[106:107], v[184:185], v[124:125], v[106:107] op_sel_hi:[0,1,1] neg_lo:[0,0,1] neg_hi:[0,0,1]
	v_mov_b32_e32 v185, v176
	v_mov_b32_e32 v177, v184
	v_mov_b32_e32 v109, v107
	v_pk_mul_f32 v[106:107], v[188:189], v[184:185]
	v_pk_mul_f32 v[112:113], v[188:189], v[176:177]
	v_mov_b32_e32 v124, v106
	v_mov_b32_e32 v125, v112
	v_mov_b32_e32 v112, v107
	v_pk_add_f32 v[106:107], v[124:125], v[112:113] neg_lo:[0,1] neg_hi:[0,1]
	v_pk_add_f32 v[112:113], v[124:125], v[112:113]
	v_mov_b32_e32 v124, v106
	v_mov_b32_e32 v125, v113
	v_pk_mul_f32 v[112:113], v[112:113], v[132:133] op_sel:[1,1] op_sel_hi:[1,0]
	s_nop 0
	v_pk_fma_f32 v[176:177], v[106:107], v[132:133], v[112:113]
	v_pk_fma_f32 v[106:107], v[106:107], v[132:133], v[112:113] op_sel_hi:[0,1,1] neg_lo:[0,0,1] neg_hi:[0,0,1]
	v_mov_b32_e32 v177, v107
	v_pk_mul_f32 v[106:107], v[188:189], v[124:125]
	v_pk_mul_f32 v[112:113], v[178:179], v[124:125]
	v_mov_b32_e32 v124, v106
	v_mov_b32_e32 v125, v113
	v_pk_mov_b32 v[106:107], v[106:107], v[112:113] op_sel:[1,0]
	s_nop 0
	v_pk_add_f32 v[112:113], v[124:125], v[106:107] neg_lo:[0,1] neg_hi:[0,1]
	v_pk_add_f32 v[106:107], v[124:125], v[106:107]
	v_mov_b32_e32 v124, v112
	v_mov_b32_e32 v125, v107
	v_pk_mul_f32 v[106:107], v[106:107], v[180:181] op_sel:[1,1] op_sel_hi:[1,0]
	s_nop 0
	v_pk_fma_f32 v[132:133], v[112:113], v[180:181], v[106:107]
	v_pk_fma_f32 v[106:107], v[112:113], v[180:181], v[106:107] op_sel_hi:[0,1,1] neg_lo:[0,0,1] neg_hi:[0,0,1]
	v_pk_mul_f32 v[112:113], v[178:179], v[124:125]
	v_mov_b32_e32 v133, v107
	v_pk_mul_f32 v[106:107], v[188:189], v[124:125]
	v_pk_add_f32 v[112:113], v[112:113], v[112:113] op_sel:[1,0] op_sel_hi:[1,0]
	v_pk_add_f32 v[106:107], v[106:107], v[106:107] op_sel:[0,1] op_sel_hi:[0,1] neg_lo:[0,1] neg_hi:[0,1]
	v_pk_mul_f32 v[112:113], v[112:113], v[110:111] op_sel:[0,1] op_sel_hi:[1,0]
	s_nop 0
	v_pk_fma_f32 v[124:125], v[106:107], v[110:111], v[112:113]
	v_pk_fma_f32 v[106:107], v[106:107], v[110:111], v[112:113] neg_lo:[0,0,1] neg_hi:[0,0,1]
	v_mul_f32_e32 v125, 0x41400000, v192
	v_sin_f32_e32 v180, v125
	v_cos_f32_e32 v184, v125
	v_mov_b32_e32 v125, v107
	v_pk_mul_f32 v[106:107], v[180:181], v[182:183] op_sel:[0,1] op_sel_hi:[0,0]
	v_pk_fma_f32 v[110:111], v[184:185], v[182:183], v[106:107]
	v_pk_fma_f32 v[106:107], v[184:185], v[182:183], v[106:107] op_sel_hi:[0,1,1] neg_lo:[0,0,1] neg_hi:[0,0,1]
	v_mov_b32_e32 v185, v180
	v_mov_b32_e32 v181, v184
	v_mov_b32_e32 v111, v107
	v_pk_mul_f32 v[106:107], v[188:189], v[184:185]
	v_pk_mul_f32 v[112:113], v[188:189], v[180:181]
	v_mov_b32_e32 v180, v106
	v_mov_b32_e32 v181, v112
	v_mov_b32_e32 v112, v107
	v_pk_add_f32 v[106:107], v[180:181], v[112:113] neg_lo:[0,1] neg_hi:[0,1]
	v_pk_add_f32 v[112:113], v[180:181], v[112:113]
	v_mov_b32_e32 v180, v106
	v_mov_b32_e32 v181, v113
	v_pk_mul_f32 v[112:113], v[112:113], v[118:119] op_sel:[1,1] op_sel_hi:[1,0]
	s_nop 0
	v_pk_fma_f32 v[182:183], v[106:107], v[118:119], v[112:113]
	v_pk_fma_f32 v[106:107], v[106:107], v[118:119], v[112:113] op_sel_hi:[0,1,1] neg_lo:[0,0,1] neg_hi:[0,0,1]
	v_mov_b32_e32 v183, v107
	v_pk_mul_f32 v[106:107], v[188:189], v[180:181]
	v_pk_mul_f32 v[112:113], v[178:179], v[180:181]
	v_mov_b32_e32 v118, v106
	v_mov_b32_e32 v119, v113
	v_pk_mov_b32 v[106:107], v[106:107], v[112:113] op_sel:[1,0]
	s_nop 0
	v_pk_add_f32 v[112:113], v[118:119], v[106:107] neg_lo:[0,1] neg_hi:[0,1]
	v_pk_add_f32 v[106:107], v[118:119], v[106:107]
	v_mov_b32_e32 v118, v112
	v_mov_b32_e32 v119, v107
	v_pk_mul_f32 v[106:107], v[106:107], v[128:129] op_sel:[1,1] op_sel_hi:[1,0]
	s_nop 0
	v_pk_fma_f32 v[180:181], v[112:113], v[128:129], v[106:107]
	v_pk_fma_f32 v[106:107], v[112:113], v[128:129], v[106:107] op_sel_hi:[0,1,1] neg_lo:[0,0,1] neg_hi:[0,0,1]
	v_pk_mul_f32 v[112:113], v[178:179], v[118:119]
	v_mov_b32_e32 v181, v107
	v_pk_mul_f32 v[106:107], v[188:189], v[118:119]
	v_pk_add_f32 v[112:113], v[112:113], v[112:113] op_sel:[1,0] op_sel_hi:[1,0]
	v_pk_add_f32 v[106:107], v[106:107], v[106:107] op_sel:[0,1] op_sel_hi:[0,1] neg_lo:[0,1] neg_hi:[0,1]
	v_pk_mul_f32 v[112:113], v[112:113], v[120:121] op_sel:[0,1] op_sel_hi:[1,0]
	s_nop 0
	v_pk_fma_f32 v[118:119], v[106:107], v[120:121], v[112:113]
	v_pk_fma_f32 v[106:107], v[106:107], v[120:121], v[112:113] neg_lo:[0,0,1] neg_hi:[0,0,1]
	s_nop 0
	v_mov_b32_e32 v119, v107
	ds_write_b64 v207, v[104:105]
	ds_write_b64 v207, v[130:131] offset:2176
	ds_write_b64 v207, v[190:191] offset:4352
	ds_write_b64 v207, v[122:123] offset:6528
	ds_write_b64 v207, v[134:135] offset:8704
	ds_write_b64 v207, v[126:127] offset:10880
	ds_write_b64 v207, v[116:117] offset:13056
	ds_write_b64 v207, v[114:115] offset:15232
	ds_write_b64 v207, v[108:109] offset:17408
	ds_write_b64 v207, v[176:177] offset:19584
	ds_write_b64 v207, v[132:133] offset:21760
	ds_write_b64 v207, v[124:125] offset:23936
	ds_write_b64 v207, v[110:111] offset:26112
	ds_write_b64 v207, v[182:183] offset:28288
	ds_write_b64 v207, v[180:181] offset:30464
	ds_write_b64 v207, v[118:119] offset:32640
	v_mov_b32_e32 v104, v208
	s_waitcnt lgkmcnt(0)
	s_barrier
	s_nop 0
	v_and_b32_e32 v206, 15, v104
	v_lshlrev_b32_e32 v104, 4, v104
	v_and_b32_e32 v104, 0xffffff00, v104
	v_ashrrev_i32_e32 v105, 1, v104
	v_add_u32_e32 v105, s35, v105
	v_lshlrev_b32_e32 v104, 3, v104
	v_lshlrev_b32_e32 v106, 3, v206
	v_add3_u32 v207, v105, v104, v106
	ds_read2_b64 v[106:109], v207 offset1:17
	ds_read2_b64 v[110:113], v207 offset0:34 offset1:51
	ds_read2_b64 v[114:117], v207 offset0:68 offset1:85
	ds_read2_b64 v[118:121], v207 offset0:136 offset1:153
	ds_read2_b64 v[122:125], v207 offset0:204 offset1:221
	ds_read2_b64 v[126:129], v207 offset0:102 offset1:119
	ds_read2_b64 v[130:133], v207 offset0:170 offset1:187
	ds_read2_b64 v[176:179], v207 offset0:238 offset1:255
	s_waitcnt lgkmcnt(4)
	v_pk_add_f32 v[192:193], v[108:109], v[120:121]
	s_waitcnt lgkmcnt(3)
	v_pk_add_f32 v[180:181], v[114:115], v[122:123]
	v_pk_add_f32 v[194:195], v[116:117], v[124:125]
	v_pk_add_f32 v[114:115], v[114:115], v[122:123] neg_lo:[0,1] neg_hi:[0,1]
	s_waitcnt lgkmcnt(0)
	v_pk_add_f32 v[122:123], v[126:127], v[176:177] neg_lo:[0,1] neg_hi:[0,1]
	v_pk_add_f32 v[116:117], v[116:117], v[124:125] neg_lo:[0,1] neg_hi:[0,1]
	v_pk_add_f32 v[184:185], v[110:111], v[130:131]
	v_pk_add_f32 v[186:187], v[126:127], v[176:177]
	v_pk_add_f32 v[110:111], v[110:111], v[130:131] neg_lo:[0,1] neg_hi:[0,1]
	v_xor_b32_e32 v127, 0x80000000, v122
	v_mov_b32_e32 v126, v123
	v_pk_add_f32 v[108:109], v[108:109], v[120:121] neg_lo:[0,1] neg_hi:[0,1]
	v_xor_b32_e32 v121, 0x80000000, v116
	v_mov_b32_e32 v120, v117
	v_pk_add_f32 v[122:123], v[110:111], v[126:127]
	v_pk_add_f32 v[116:117], v[108:109], v[120:121]
	v_pk_mul_f32 v[130:131], v[122:123], s[24:25] op_sel_hi:[1,0]
	v_pk_mul_f32 v[124:125], v[116:117], s[30:31] op_sel_hi:[1,0]
	v_pk_fma_f32 v[176:177], v[122:123], s[24:25], v[130:131] op_sel:[0,0,1] op_sel_hi:[1,0,0]
	v_pk_fma_f32 v[122:123], v[122:123], s[24:25], v[130:131] op_sel_hi:[1,0,0] neg_lo:[0,0,1] neg_hi:[0,0,1]
	v_pk_fma_f32 v[130:131], v[116:117], s[22:23], v[124:125] op_sel:[0,0,1] op_sel_hi:[1,0,0]
	v_pk_fma_f32 v[116:117], v[116:117], s[22:23], v[124:125] op_sel:[0,0,1] op_sel_hi:[1,0,0] neg_lo:[0,0,1] neg_hi:[0,0,1]
	v_pk_add_f32 v[188:189], v[184:185], v[186:187]
	v_pk_add_f32 v[200:201], v[128:129], v[178:179]
	v_mov_b32_e32 v131, v117
	v_pk_add_f32 v[116:117], v[128:129], v[178:179] neg_lo:[0,1] neg_hi:[0,1]
	v_pk_add_f32 v[178:179], v[184:185], v[186:187] neg_lo:[0,1] neg_hi:[0,1]
	v_pk_add_f32 v[184:185], v[192:193], v[194:195] neg_lo:[0,1] neg_hi:[0,1]
	v_pk_add_f32 v[198:199], v[112:113], v[132:133]
	v_pk_add_f32 v[112:113], v[112:113], v[132:133] neg_lo:[0,1] neg_hi:[0,1]
	v_xor_b32_e32 v125, 0x80000000, v116
	v_mov_b32_e32 v124, v117
	v_pk_mul_f32 v[186:187], v[184:185], s[24:25] op_sel_hi:[1,0]
	v_pk_add_f32 v[196:197], v[192:193], v[194:195]
	v_pk_add_f32 v[116:117], v[112:113], v[124:125]
	v_pk_fma_f32 v[192:193], v[184:185], s[24:25], v[186:187] op_sel:[0,0,1] op_sel_hi:[1,0,0]
	v_pk_fma_f32 v[184:185], v[184:185], s[24:25], v[186:187] op_sel_hi:[1,0,0] neg_lo:[0,0,1] neg_hi:[0,0,1]
	v_pk_mul_f32 v[128:129], v[116:117], s[22:23] op_sel_hi:[1,0]
	v_mov_b32_e32 v193, v185
	v_pk_add_f32 v[184:185], v[198:199], v[200:201] neg_lo:[0,1] neg_hi:[0,1]
	v_pk_fma_f32 v[132:133], v[116:117], s[30:31], v[128:129] op_sel:[0,0,1] op_sel_hi:[1,0,0]
	v_pk_fma_f32 v[116:117], v[116:117], s[30:31], v[128:129] op_sel:[0,0,1] op_sel_hi:[1,0,0] neg_lo:[0,0,1] neg_hi:[0,0,1]
	v_mul_f32_e32 v186, 0x3f3504f3, v184
	v_pk_add_f32 v[134:135], v[106:107], v[118:119]
	v_pk_add_f32 v[106:107], v[106:107], v[118:119] neg_lo:[0,1] neg_hi:[0,1]
	v_xor_b32_e32 v119, 0x80000000, v114
	v_mov_b32_e32 v118, v115
	v_mov_b32_e32 v133, v117
	v_pk_fma_f32 v[184:185], v[184:185], s[24:25], v[186:187] op_sel:[1,0,0] op_sel_hi:[1,1,0] neg_lo:[0,0,1] neg_hi:[0,0,1]
	v_pk_add_f32 v[108:109], v[108:109], v[120:121] neg_lo:[0,1] neg_hi:[0,1]
	v_pk_add_f32 v[182:183], v[134:135], v[180:181]
	v_pk_add_f32 v[114:115], v[106:107], v[118:119]
	v_mov_b32_e32 v177, v123
	v_pk_add_f32 v[116:117], v[130:131], v[132:133] neg_lo:[0,1] neg_hi:[0,1]
	v_pk_add_f32 v[134:135], v[134:135], v[180:181] neg_lo:[0,1] neg_hi:[0,1]
	v_xor_b32_e32 v181, 0x80000000, v178
	v_mov_b32_e32 v180, v179
	v_pk_add_f32 v[186:187], v[192:193], v[184:185] neg_lo:[0,1] neg_hi:[0,1]
	v_pk_mul_f32 v[120:121], v[108:109], s[22:23] op_sel_hi:[1,0]
	v_pk_add_f32 v[122:123], v[114:115], v[176:177] neg_lo:[0,1] neg_hi:[0,1]
	v_xor_b32_e32 v129, 0x80000000, v116
	v_mov_b32_e32 v128, v117
	v_pk_add_f32 v[178:179], v[134:135], v[180:181] neg_lo:[0,1] neg_hi:[0,1]
	v_xor_b32_e32 v195, 0x80000000, v186
	v_mov_b32_e32 v194, v187
	v_pk_add_f32 v[110:111], v[110:111], v[126:127] neg_lo:[0,1] neg_hi:[0,1]
	v_pk_fma_f32 v[126:127], v[108:109], s[30:31], v[120:121] op_sel:[0,0,1] op_sel_hi:[1,0,0]
	v_pk_fma_f32 v[108:109], v[108:109], s[30:31], v[120:121] op_sel:[0,0,1] op_sel_hi:[1,0,0] neg_lo:[0,0,1] neg_hi:[0,0,1]
	v_pk_add_f32 v[116:117], v[122:123], v[128:129]
	v_pk_add_f32 v[186:187], v[178:179], v[194:195]
	v_mov_b32_e32 v127, v109
	v_pk_add_f32 v[108:109], v[112:113], v[124:125] neg_lo:[0,1] neg_hi:[0,1]
	v_pk_add_f32 v[122:123], v[122:123], v[128:129] neg_lo:[0,1] neg_hi:[0,1]
	v_pk_add_f32 v[128:129], v[178:179], v[194:195] neg_lo:[0,1] neg_hi:[0,1]
	v_cvt_f32_ubyte0_e32 v178, v206
	v_pk_mul_f32 v[112:113], v[108:109], s[30:31]
	v_pk_add_f32 v[114:115], v[114:115], v[176:177]
	v_pk_add_f32 v[176:177], v[192:193], v[184:185]
	v_mul_f32_e32 v192, 0x3b800000, v178
	v_pk_fma_f32 v[108:109], v[108:109], s[22:23], v[112:113] op_sel:[0,0,1] op_sel_hi:[1,0,0] neg_lo:[1,0,0] neg_hi:[1,0,0]
	v_sin_f32_e32 v178, v192
	v_pk_add_f32 v[190:191], v[182:183], v[188:189]
	v_pk_add_f32 v[106:107], v[106:107], v[118:119] neg_lo:[0,1] neg_hi:[0,1]
	v_mul_f32_e32 v118, 0x3f3504f3, v110
	v_pk_add_f32 v[112:113], v[126:127], v[108:109] neg_lo:[0,1] neg_hi:[0,1]
	v_pk_add_f32 v[108:109], v[126:127], v[108:109]
	v_pk_add_f32 v[126:127], v[182:183], v[188:189] neg_lo:[0,1] neg_hi:[0,1]
	v_cos_f32_e32 v188, v192
	v_pk_fma_f32 v[110:111], v[110:111], s[24:25], v[118:119] op_sel:[1,0,0] op_sel_hi:[1,1,0] neg_lo:[0,0,1] neg_hi:[0,0,1]
	v_pk_add_f32 v[130:131], v[130:131], v[132:133]
	v_pk_add_f32 v[118:119], v[106:107], v[110:111] neg_lo:[0,1] neg_hi:[0,1]
	v_xor_b32_e32 v121, 0x80000000, v112
	v_mov_b32_e32 v120, v113
	v_pk_add_f32 v[132:133], v[114:115], v[130:131] neg_lo:[0,1] neg_hi:[0,1]
	v_pk_add_f32 v[114:115], v[114:115], v[130:131]
	v_pk_add_f32 v[112:113], v[118:119], v[120:121]
	v_pk_add_f32 v[118:119], v[118:119], v[120:121] neg_lo:[0,1] neg_hi:[0,1]
	v_pk_mul_f32 v[120:121], v[178:179], v[114:115] op_sel:[0,1] op_sel_hi:[0,0]
	v_pk_add_f32 v[134:135], v[134:135], v[180:181]
	v_pk_fma_f32 v[130:131], v[188:189], v[114:115], v[120:121]
	v_pk_fma_f32 v[114:115], v[188:189], v[114:115], v[120:121] op_sel_hi:[0,1,1] neg_lo:[0,0,1] neg_hi:[0,0,1]
	v_mov_b32_e32 v189, v178
	v_pk_add_f32 v[180:181], v[134:135], v[176:177] neg_lo:[0,1] neg_hi:[0,1]
	v_mov_b32_e32 v131, v115
	v_pk_mul_f32 v[114:115], v[188:189], v[188:189]
	v_pk_add_f32 v[120:121], v[134:135], v[176:177]
	v_mul_f32_e32 v135, v188, v178
	v_mov_b32_e32 v134, v114
	v_mov_b32_e32 v114, v115
	v_mov_b32_e32 v115, v135
	v_pk_add_f32 v[202:203], v[198:199], v[200:201]
	v_pk_add_f32 v[176:177], v[134:135], v[114:115] neg_lo:[0,1] neg_hi:[0,1]
	v_pk_add_f32 v[114:115], v[134:135], v[114:115]
	v_pk_add_f32 v[204:205], v[196:197], v[202:203]
	v_pk_add_f32 v[106:107], v[106:107], v[110:111]
	v_mov_b32_e32 v134, v176
	v_mov_b32_e32 v135, v115
	v_pk_mul_f32 v[114:115], v[114:115], v[120:121] op_sel:[1,1] op_sel_hi:[1,0]
	v_mov_b32_e32 v179, v188
	v_pk_add_f32 v[104:105], v[190:191], v[204:205]
	v_pk_add_f32 v[124:125], v[190:191], v[204:205] neg_lo:[0,1] neg_hi:[0,1]
	v_pk_add_f32 v[110:111], v[106:107], v[108:109] neg_lo:[0,1] neg_hi:[0,1]
	v_pk_fma_f32 v[190:191], v[176:177], v[120:121], v[114:115]
	v_pk_fma_f32 v[114:115], v[176:177], v[120:121], v[114:115] op_sel_hi:[0,1,1] neg_lo:[0,0,1] neg_hi:[0,0,1]
	v_pk_add_f32 v[106:107], v[106:107], v[108:109]
	v_pk_mul_f32 v[108:109], v[178:179], v[134:135]
	v_mov_b32_e32 v191, v115
	v_pk_mul_f32 v[114:115], v[188:189], v[134:135]
	v_pk_add_f32 v[108:109], v[108:109], v[108:109] op_sel:[1,0] op_sel_hi:[1,0]
	v_pk_add_f32 v[114:115], v[114:115], v[114:115] op_sel:[0,1] op_sel_hi:[0,1] neg_lo:[0,1] neg_hi:[0,1]
	v_pk_mul_f32 v[108:109], v[108:109], v[106:107] op_sel:[0,1] op_sel_hi:[1,0]
	v_pk_add_f32 v[182:183], v[196:197], v[202:203] neg_lo:[0,1] neg_hi:[0,1]
	v_pk_fma_f32 v[120:121], v[114:115], v[106:107], v[108:109]
	v_pk_fma_f32 v[106:107], v[114:115], v[106:107], v[108:109] neg_lo:[0,0,1] neg_hi:[0,0,1]
	v_mul_f32_e32 v108, 4.0, v192
	v_sin_f32_e32 v106, v108
	v_cos_f32_e32 v108, v108
	v_xor_b32_e32 v185, 0x80000000, v182
	v_mov_b32_e32 v184, v183
	v_pk_add_f32 v[114:115], v[126:127], v[184:185]
	v_pk_add_f32 v[182:183], v[126:127], v[184:185] neg_lo:[0,1] neg_hi:[0,1]
	v_pk_mul_f32 v[126:127], v[106:107], v[114:115] op_sel:[0,1] op_sel_hi:[0,0]
	v_mov_b32_e32 v121, v107
	v_pk_fma_f32 v[134:135], v[108:109], v[114:115], v[126:127]
	v_pk_fma_f32 v[114:115], v[108:109], v[114:115], v[126:127] op_sel_hi:[0,1,1] neg_lo:[0,0,1] neg_hi:[0,0,1]
	v_mov_b32_e32 v109, v106
	v_mov_b32_e32 v107, v108
	v_mov_b32_e32 v135, v115
	v_pk_mul_f32 v[114:115], v[188:189], v[108:109]
	v_pk_mul_f32 v[106:107], v[188:189], v[106:107]
	v_mov_b32_e32 v108, v114
	v_mov_b32_e32 v109, v106
	v_mov_b32_e32 v106, v115
	v_pk_add_f32 v[114:115], v[108:109], v[106:107] neg_lo:[0,1] neg_hi:[0,1]
	v_pk_add_f32 v[106:107], v[108:109], v[106:107]
	v_mov_b32_e32 v108, v114
	v_mov_b32_e32 v109, v107
	v_pk_mul_f32 v[106:107], v[106:107], v[116:117] op_sel:[1,1] op_sel_hi:[1,0]
	s_nop 0
	v_pk_fma_f32 v[126:127], v[114:115], v[116:117], v[106:107]
	v_pk_fma_f32 v[106:107], v[114:115], v[116:117], v[106:107] op_sel_hi:[0,1,1] neg_lo:[0,0,1] neg_hi:[0,0,1]
	v_mov_b32_e32 v127, v107
	v_pk_mul_f32 v[106:107], v[188:189], v[108:109]
	v_pk_mul_f32 v[108:109], v[178:179], v[108:109]
	v_mov_b32_e32 v114, v106
	v_mov_b32_e32 v115, v109
	v_pk_mov_b32 v[106:107], v[106:107], v[108:109] op_sel:[1,0]
	s_nop 0
	v_pk_add_f32 v[108:109], v[114:115], v[106:107] neg_lo:[0,1] neg_hi:[0,1]
	v_pk_add_f32 v[106:107], v[114:115], v[106:107]
	v_mov_b32_e32 v114, v108
	v_mov_b32_e32 v115, v107
	v_pk_mul_f32 v[106:107], v[106:107], v[186:187] op_sel:[1,1] op_sel_hi:[1,0]
	s_nop 0
	v_pk_fma_f32 v[116:117], v[108:109], v[186:187], v[106:107]
	v_pk_fma_f32 v[106:107], v[108:109], v[186:187], v[106:107] op_sel_hi:[0,1,1] neg_lo:[0,0,1] neg_hi:[0,0,1]
	v_pk_mul_f32 v[108:109], v[178:179], v[114:115]
	v_mov_b32_e32 v117, v107
	v_pk_mul_f32 v[106:107], v[188:189], v[114:115]
	v_pk_add_f32 v[108:109], v[108:109], v[108:109] op_sel:[1,0] op_sel_hi:[1,0]
	v_pk_add_f32 v[106:107], v[106:107], v[106:107] op_sel:[0,1] op_sel_hi:[0,1] neg_lo:[0,1] neg_hi:[0,1]
	v_pk_mul_f32 v[108:109], v[108:109], v[112:113] op_sel:[0,1] op_sel_hi:[1,0]
	s_nop 0
	v_pk_fma_f32 v[114:115], v[106:107], v[112:113], v[108:109]
	v_pk_fma_f32 v[106:107], v[106:107], v[112:113], v[108:109] neg_lo:[0,0,1] neg_hi:[0,0,1]
	v_mul_f32_e32 v115, 0x41000000, v192
	v_sin_f32_e32 v176, v115
	v_cos_f32_e32 v184, v115
	v_mov_b32_e32 v115, v107
	v_pk_mul_f32 v[106:107], v[176:177], v[124:125] op_sel:[0,1] op_sel_hi:[0,0]
	v_pk_fma_f32 v[108:109], v[184:185], v[124:125], v[106:107]
	v_pk_fma_f32 v[106:107], v[184:185], v[124:125], v[106:107] op_sel_hi:[0,1,1] neg_lo:[0,0,1] neg_hi:[0,0,1]
	v_mov_b32_e32 v185, v176
	v_mov_b32_e32 v177, v184
	v_mov_b32_e32 v109, v107
	v_pk_mul_f32 v[106:107], v[188:189], v[184:185]
	v_pk_mul_f32 v[112:113], v[188:189], v[176:177]
	v_mov_b32_e32 v124, v106
	v_mov_b32_e32 v125, v112
	v_mov_b32_e32 v112, v107
	v_pk_add_f32 v[106:107], v[124:125], v[112:113] neg_lo:[0,1] neg_hi:[0,1]
	v_pk_add_f32 v[112:113], v[124:125], v[112:113]
	v_mov_b32_e32 v124, v106
	v_mov_b32_e32 v125, v113
	v_pk_mul_f32 v[112:113], v[112:113], v[132:133] op_sel:[1,1] op_sel_hi:[1,0]
	s_nop 0
	v_pk_fma_f32 v[176:177], v[106:107], v[132:133], v[112:113]
	v_pk_fma_f32 v[106:107], v[106:107], v[132:133], v[112:113] op_sel_hi:[0,1,1] neg_lo:[0,0,1] neg_hi:[0,0,1]
	v_mov_b32_e32 v177, v107
	v_pk_mul_f32 v[106:107], v[188:189], v[124:125]
	v_pk_mul_f32 v[112:113], v[178:179], v[124:125]
	v_mov_b32_e32 v124, v106
	v_mov_b32_e32 v125, v113
	v_pk_mov_b32 v[106:107], v[106:107], v[112:113] op_sel:[1,0]
	s_nop 0
	v_pk_add_f32 v[112:113], v[124:125], v[106:107] neg_lo:[0,1] neg_hi:[0,1]
	v_pk_add_f32 v[106:107], v[124:125], v[106:107]
	v_mov_b32_e32 v124, v112
	v_mov_b32_e32 v125, v107
	v_pk_mul_f32 v[106:107], v[106:107], v[180:181] op_sel:[1,1] op_sel_hi:[1,0]
	s_nop 0
	v_pk_fma_f32 v[132:133], v[112:113], v[180:181], v[106:107]
	v_pk_fma_f32 v[106:107], v[112:113], v[180:181], v[106:107] op_sel_hi:[0,1,1] neg_lo:[0,0,1] neg_hi:[0,0,1]
	v_pk_mul_f32 v[112:113], v[178:179], v[124:125]
	v_mov_b32_e32 v133, v107
	v_pk_mul_f32 v[106:107], v[188:189], v[124:125]
	v_pk_add_f32 v[112:113], v[112:113], v[112:113] op_sel:[1,0] op_sel_hi:[1,0]
	v_pk_add_f32 v[106:107], v[106:107], v[106:107] op_sel:[0,1] op_sel_hi:[0,1] neg_lo:[0,1] neg_hi:[0,1]
	v_pk_mul_f32 v[112:113], v[112:113], v[110:111] op_sel:[0,1] op_sel_hi:[1,0]
	s_nop 0
	v_pk_fma_f32 v[124:125], v[106:107], v[110:111], v[112:113]
	v_pk_fma_f32 v[106:107], v[106:107], v[110:111], v[112:113] neg_lo:[0,0,1] neg_hi:[0,0,1]
	v_mul_f32_e32 v125, 0x41400000, v192
	v_sin_f32_e32 v180, v125
	v_cos_f32_e32 v184, v125
	v_mov_b32_e32 v125, v107
	v_pk_mul_f32 v[106:107], v[180:181], v[182:183] op_sel:[0,1] op_sel_hi:[0,0]
	v_pk_fma_f32 v[110:111], v[184:185], v[182:183], v[106:107]
	v_pk_fma_f32 v[106:107], v[184:185], v[182:183], v[106:107] op_sel_hi:[0,1,1] neg_lo:[0,0,1] neg_hi:[0,0,1]
	v_mov_b32_e32 v185, v180
	v_mov_b32_e32 v181, v184
	v_mov_b32_e32 v111, v107
	v_pk_mul_f32 v[106:107], v[188:189], v[184:185]
	v_pk_mul_f32 v[112:113], v[188:189], v[180:181]
	v_mov_b32_e32 v180, v106
	v_mov_b32_e32 v181, v112
	v_mov_b32_e32 v112, v107
	v_pk_add_f32 v[106:107], v[180:181], v[112:113] neg_lo:[0,1] neg_hi:[0,1]
	v_pk_add_f32 v[112:113], v[180:181], v[112:113]
	v_mov_b32_e32 v180, v106
	v_mov_b32_e32 v181, v113
	v_pk_mul_f32 v[112:113], v[112:113], v[122:123] op_sel:[1,1] op_sel_hi:[1,0]
	s_nop 0
	v_pk_fma_f32 v[182:183], v[106:107], v[122:123], v[112:113]
	v_pk_fma_f32 v[106:107], v[106:107], v[122:123], v[112:113] op_sel_hi:[0,1,1] neg_lo:[0,0,1] neg_hi:[0,0,1]
	v_mov_b32_e32 v183, v107
	v_pk_mul_f32 v[106:107], v[188:189], v[180:181]
	v_pk_mul_f32 v[112:113], v[178:179], v[180:181]
	v_mov_b32_e32 v122, v106
	v_mov_b32_e32 v123, v113
	v_pk_mov_b32 v[106:107], v[106:107], v[112:113] op_sel:[1,0]
	s_nop 0
	v_pk_add_f32 v[112:113], v[122:123], v[106:107] neg_lo:[0,1] neg_hi:[0,1]
	v_pk_add_f32 v[106:107], v[122:123], v[106:107]
	v_mov_b32_e32 v122, v112
	v_mov_b32_e32 v123, v107
	v_pk_mul_f32 v[106:107], v[106:107], v[128:129] op_sel:[1,1] op_sel_hi:[1,0]
	s_nop 0
	v_pk_fma_f32 v[180:181], v[112:113], v[128:129], v[106:107]
	v_pk_fma_f32 v[106:107], v[112:113], v[128:129], v[106:107] op_sel_hi:[0,1,1] neg_lo:[0,0,1] neg_hi:[0,0,1]
	v_pk_mul_f32 v[112:113], v[178:179], v[122:123]
	v_mov_b32_e32 v181, v107
	v_pk_mul_f32 v[106:107], v[188:189], v[122:123]
	v_pk_add_f32 v[112:113], v[112:113], v[112:113] op_sel:[1,0] op_sel_hi:[1,0]
	v_pk_add_f32 v[106:107], v[106:107], v[106:107] op_sel:[0,1] op_sel_hi:[0,1] neg_lo:[0,1] neg_hi:[0,1]
	v_pk_mul_f32 v[112:113], v[112:113], v[118:119] op_sel:[0,1] op_sel_hi:[1,0]
	s_nop 0
	v_pk_fma_f32 v[122:123], v[106:107], v[118:119], v[112:113]
	v_pk_fma_f32 v[106:107], v[106:107], v[118:119], v[112:113] neg_lo:[0,0,1] neg_hi:[0,0,1]
	s_nop 0
	v_mov_b32_e32 v123, v107
	ds_write2_b64 v207, v[104:105], v[130:131] offset1:17
	ds_write2_b64 v207, v[190:191], v[120:121] offset0:34 offset1:51
	ds_write2_b64 v207, v[134:135], v[126:127] offset0:68 offset1:85
	ds_write2_b64 v207, v[116:117], v[114:115] offset0:102 offset1:119
	ds_write2_b64 v207, v[108:109], v[176:177] offset0:136 offset1:153
	ds_write2_b64 v207, v[132:133], v[124:125] offset0:170 offset1:187
	ds_write2_b64 v207, v[110:111], v[182:183] offset0:204 offset1:221
	ds_write2_b64 v207, v[180:181], v[122:123] offset0:238 offset1:255
	v_mov_b32_e32 v104, v208
	s_waitcnt lgkmcnt(0)
	s_nop 0
	v_lshlrev_b32_e32 v105, 4, v104
	v_bfe_i32 v104, v104, 0, 28
	v_add_lshl_u32 v182, v104, v105, 3
	v_add_u32_e32 v188, s35, v182
	ds_read2_b64 v[104:107], v188 offset1:1
	ds_read2_b64 v[108:111], v188 offset0:2 offset1:3
	ds_read2_b64 v[112:115], v188 offset0:8 offset1:9
	ds_read2_b64 v[116:119], v188 offset0:4 offset1:5
	ds_read2_b64 v[120:123], v188 offset0:6 offset1:7
	ds_read2_b64 v[124:127], v188 offset0:12 offset1:13
	ds_read2_b64 v[128:131], v188 offset0:10 offset1:11
	ds_read2_b64 v[132:135], v188 offset0:14 offset1:15
	s_waitcnt lgkmcnt(5)
	v_pk_add_f32 v[176:177], v[104:105], v[112:113]
	v_pk_add_f32 v[104:105], v[104:105], v[112:113] neg_lo:[0,1] neg_hi:[0,1]
	s_waitcnt lgkmcnt(2)
	v_pk_add_f32 v[112:113], v[116:117], v[124:125]
	v_pk_add_f32 v[116:117], v[116:117], v[124:125] neg_lo:[0,1] neg_hi:[0,1]
	v_add_u32_e32 v189, 0, v182
	v_xor_b32_e32 v125, 0x80000000, v116
	v_mov_b32_e32 v124, v117
	v_pk_add_f32 v[116:117], v[176:177], v[112:113]
	v_pk_add_f32 v[112:113], v[176:177], v[112:113] neg_lo:[0,1] neg_hi:[0,1]
	v_pk_add_f32 v[176:177], v[104:105], v[124:125]
	v_pk_add_f32 v[104:105], v[104:105], v[124:125] neg_lo:[0,1] neg_hi:[0,1]
	v_pk_add_f32 v[124:125], v[106:107], v[114:115]
	v_pk_add_f32 v[106:107], v[106:107], v[114:115] neg_lo:[0,1] neg_hi:[0,1]
	v_pk_add_f32 v[114:115], v[118:119], v[126:127]
	v_pk_add_f32 v[118:119], v[118:119], v[126:127] neg_lo:[0,1] neg_hi:[0,1]
	s_nop 0
	v_xor_b32_e32 v127, 0x80000000, v118
	v_mov_b32_e32 v126, v119
	v_pk_add_f32 v[118:119], v[124:125], v[114:115]
	v_pk_add_f32 v[114:115], v[124:125], v[114:115] neg_lo:[0,1] neg_hi:[0,1]
	v_pk_add_f32 v[124:125], v[106:107], v[126:127]
	v_pk_add_f32 v[106:107], v[106:107], v[126:127] neg_lo:[0,1] neg_hi:[0,1]
	s_waitcnt lgkmcnt(1)
	v_pk_add_f32 v[126:127], v[108:109], v[128:129]
	v_pk_add_f32 v[108:109], v[108:109], v[128:129] neg_lo:[0,1] neg_hi:[0,1]
	s_waitcnt lgkmcnt(0)
	v_pk_add_f32 v[128:129], v[120:121], v[132:133]
	v_pk_add_f32 v[120:121], v[120:121], v[132:133] neg_lo:[0,1] neg_hi:[0,1]
	s_nop 0
	v_xor_b32_e32 v133, 0x80000000, v120
	v_mov_b32_e32 v132, v121
	v_pk_add_f32 v[120:121], v[126:127], v[128:129]
	v_pk_add_f32 v[126:127], v[126:127], v[128:129] neg_lo:[0,1] neg_hi:[0,1]
	v_pk_add_f32 v[128:129], v[108:109], v[132:133]
	v_pk_add_f32 v[108:109], v[108:109], v[132:133] neg_lo:[0,1] neg_hi:[0,1]
	v_pk_add_f32 v[132:133], v[110:111], v[130:131]
	v_pk_add_f32 v[110:111], v[110:111], v[130:131] neg_lo:[0,1] neg_hi:[0,1]
	v_pk_add_f32 v[130:131], v[122:123], v[134:135]
	v_pk_add_f32 v[122:123], v[122:123], v[134:135] neg_lo:[0,1] neg_hi:[0,1]
	s_nop 0
	v_xor_b32_e32 v135, 0x80000000, v122
	v_mov_b32_e32 v134, v123
	v_pk_add_f32 v[122:123], v[132:133], v[130:131]
	v_pk_add_f32 v[130:131], v[132:133], v[130:131] neg_lo:[0,1] neg_hi:[0,1]
	v_pk_add_f32 v[132:133], v[110:111], v[134:135]
	v_pk_add_f32 v[110:111], v[110:111], v[134:135] neg_lo:[0,1] neg_hi:[0,1]
	v_pk_mul_f32 v[134:135], v[124:125], s[30:31] op_sel_hi:[1,0]
	s_nop 0
	v_pk_fma_f32 v[178:179], v[124:125], s[22:23], v[134:135] op_sel:[0,0,1] op_sel_hi:[1,0,0]
	v_pk_fma_f32 v[124:125], v[124:125], s[22:23], v[134:135] op_sel:[0,0,1] op_sel_hi:[1,0,0] neg_lo:[0,0,1] neg_hi:[0,0,1]
	s_nop 0
	v_mov_b32_e32 v179, v125
	v_pk_mul_f32 v[124:125], v[114:115], s[24:25] op_sel_hi:[1,0]
	s_nop 0
	v_pk_fma_f32 v[134:135], v[114:115], s[24:25], v[124:125] op_sel:[0,0,1] op_sel_hi:[1,0,0]
	v_pk_fma_f32 v[114:115], v[114:115], s[24:25], v[124:125] op_sel_hi:[1,0,0] neg_lo:[0,0,1] neg_hi:[0,0,1]
	s_nop 0
	v_mov_b32_e32 v135, v115
	v_pk_mul_f32 v[114:115], v[106:107], s[22:23] op_sel_hi:[1,0]
	s_nop 0
	v_pk_fma_f32 v[124:125], v[106:107], s[30:31], v[114:115] op_sel:[0,0,1] op_sel_hi:[1,0,0]
	v_pk_fma_f32 v[106:107], v[106:107], s[30:31], v[114:115] op_sel:[0,0,1] op_sel_hi:[1,0,0] neg_lo:[0,0,1] neg_hi:[0,0,1]
	s_nop 0
	v_mov_b32_e32 v125, v107
	v_pk_mul_f32 v[106:107], v[128:129], s[24:25] op_sel_hi:[1,0]
	s_nop 0
	v_pk_fma_f32 v[114:115], v[128:129], s[24:25], v[106:107] op_sel:[0,0,1] op_sel_hi:[1,0,0]
	v_pk_fma_f32 v[106:107], v[128:129], s[24:25], v[106:107] op_sel_hi:[1,0,0] neg_lo:[0,0,1] neg_hi:[0,0,1]
	s_nop 0
	v_mov_b32_e32 v115, v107
	v_xor_b32_e32 v107, 0x80000000, v126
	v_mul_f32_e32 v126, 0x3f3504f3, v108
	v_mov_b32_e32 v106, v127
	v_pk_fma_f32 v[108:109], v[108:109], s[24:25], v[126:127] op_sel:[1,0,0] op_sel_hi:[1,1,0] neg_lo:[0,0,1] neg_hi:[0,0,1]
	v_pk_mul_f32 v[126:127], v[132:133], s[22:23] op_sel_hi:[1,0]
	s_nop 0
	v_pk_fma_f32 v[128:129], v[132:133], s[30:31], v[126:127] op_sel:[0,0,1] op_sel_hi:[1,0,0]
	v_pk_fma_f32 v[126:127], v[132:133], s[30:31], v[126:127] op_sel:[0,0,1] op_sel_hi:[1,0,0] neg_lo:[0,0,1] neg_hi:[0,0,1]
	s_nop 0
	v_mul_f32_e32 v126, 0x3f3504f3, v130
	v_mov_b32_e32 v129, v127
	v_pk_fma_f32 v[126:127], v[130:131], s[24:25], v[126:127] op_sel:[1,0,0] op_sel_hi:[1,1,0] neg_lo:[0,0,1] neg_hi:[0,0,1]
	v_pk_mul_f32 v[130:131], v[110:111], s[30:31]
	v_pk_add_f32 v[132:133], v[178:179], v[128:129]
	v_pk_fma_f32 v[110:111], v[110:111], s[22:23], v[130:131] op_sel:[0,0,1] op_sel_hi:[1,0,0] neg_lo:[1,0,0] neg_hi:[1,0,0]
	v_pk_add_f32 v[130:131], v[116:117], v[120:121]
	v_pk_add_f32 v[116:117], v[116:117], v[120:121] neg_lo:[0,1] neg_hi:[0,1]
	v_pk_add_f32 v[120:121], v[118:119], v[122:123]
	v_pk_add_f32 v[118:119], v[118:119], v[122:123] neg_lo:[0,1] neg_hi:[0,1]
	v_pk_add_f32 v[128:129], v[178:179], v[128:129] neg_lo:[0,1] neg_hi:[0,1]
	v_xor_b32_e32 v123, 0x80000000, v118
	v_mov_b32_e32 v122, v119
	v_pk_add_f32 v[118:119], v[130:131], v[120:121]
	v_pk_add_f32 v[120:121], v[130:131], v[120:121] neg_lo:[0,1] neg_hi:[0,1]
	v_pk_add_f32 v[130:131], v[116:117], v[122:123]
	v_pk_add_f32 v[116:117], v[116:117], v[122:123] neg_lo:[0,1] neg_hi:[0,1]
	v_pk_add_f32 v[122:123], v[176:177], v[114:115]
	v_pk_add_f32 v[114:115], v[176:177], v[114:115] neg_lo:[0,1] neg_hi:[0,1]
	v_xor_b32_e32 v177, 0x80000000, v128
	v_mov_b32_e32 v176, v129
	v_pk_add_f32 v[128:129], v[122:123], v[132:133]
	v_pk_add_f32 v[122:123], v[122:123], v[132:133] neg_lo:[0,1] neg_hi:[0,1]
	v_pk_add_f32 v[132:133], v[114:115], v[176:177]
	v_pk_add_f32 v[114:115], v[114:115], v[176:177] neg_lo:[0,1] neg_hi:[0,1]
	v_pk_add_f32 v[176:177], v[112:113], v[106:107]
	v_pk_add_f32 v[106:107], v[112:113], v[106:107] neg_lo:[0,1] neg_hi:[0,1]
	v_pk_add_f32 v[112:113], v[134:135], v[126:127]
	v_pk_add_f32 v[126:127], v[134:135], v[126:127] neg_lo:[0,1] neg_hi:[0,1]
	v_pk_add_f32 v[178:179], v[104:105], v[108:109]
	v_xor_b32_e32 v135, 0x80000000, v126
	v_mov_b32_e32 v134, v127
	v_pk_add_f32 v[108:109], v[104:105], v[108:109] neg_lo:[0,1] neg_hi:[0,1]
	v_pk_add_f32 v[104:105], v[124:125], v[110:111] neg_lo:[0,1] neg_hi:[0,1]
	v_pk_add_f32 v[126:127], v[176:177], v[112:113]
	v_pk_add_f32 v[112:113], v[176:177], v[112:113] neg_lo:[0,1] neg_hi:[0,1]
	v_pk_add_f32 v[176:177], v[106:107], v[134:135]
	v_pk_add_f32 v[134:135], v[106:107], v[134:135] neg_lo:[0,1] neg_hi:[0,1]
	v_pk_add_f32 v[180:181], v[124:125], v[110:111]
	v_xor_b32_e32 v111, 0x80000000, v104
	v_mov_b32_e32 v110, v105
	ds_read2_b64 v[104:107], v189 offset1:1
	v_pk_add_f32 v[124:125], v[178:179], v[180:181]
	v_pk_add_f32 v[178:179], v[178:179], v[180:181] neg_lo:[0,1] neg_hi:[0,1]
	v_pk_add_f32 v[180:181], v[108:109], v[110:111]
	v_pk_add_f32 v[182:183], v[108:109], v[110:111] neg_lo:[0,1] neg_hi:[0,1]
	ds_read2_b64 v[108:111], v189 offset0:2 offset1:3
	s_waitcnt lgkmcnt(1)
	v_pk_mul_f32 v[184:185], v[104:105], v[118:119] op_sel:[1,1] op_sel_hi:[0,1]
	v_pk_fma_f32 v[186:187], v[104:105], v[118:119], v[184:185] neg_lo:[0,0,1] neg_hi:[0,0,1]
	v_pk_fma_f32 v[104:105], v[104:105], v[118:119], v[184:185] op_sel_hi:[1,0,1]
	s_nop 0
	v_mov_b32_e32 v187, v105
	v_pk_mul_f32 v[104:105], v[106:107], v[128:129] op_sel:[1,1] op_sel_hi:[0,1]
	v_pk_fma_f32 v[184:185], v[106:107], v[128:129], v[104:105] neg_lo:[0,0,1] neg_hi:[0,0,1]
	v_pk_fma_f32 v[104:105], v[106:107], v[128:129], v[104:105] op_sel_hi:[1,0,1]
	v_pk_mul_f32 v[118:119], v[28:29], v[186:187]
	v_mov_b32_e32 v185, v105
	s_waitcnt lgkmcnt(0)
	v_pk_mul_f32 v[104:105], v[108:109], v[126:127] op_sel:[1,1] op_sel_hi:[0,1]
	v_pk_fma_f32 v[106:107], v[108:109], v[126:127], v[104:105] neg_lo:[0,0,1] neg_hi:[0,0,1]
	v_pk_fma_f32 v[104:105], v[108:109], v[126:127], v[104:105] op_sel_hi:[1,0,1]
	v_pk_mul_f32 v[108:109], v[110:111], v[124:125] op_sel:[1,1] op_sel_hi:[0,1]
	v_mov_b32_e32 v107, v105
	v_pk_mul_f32 v[126:127], v[28:29], v[106:107]
	ds_read2_b64 v[104:107], v189 offset0:4 offset1:5
	v_pk_mul_f32 v[128:129], v[28:29], v[184:185]
	v_pk_fma_f32 v[184:185], v[110:111], v[124:125], v[108:109] neg_lo:[0,0,1] neg_hi:[0,0,1]
	v_pk_fma_f32 v[108:109], v[110:111], v[124:125], v[108:109] op_sel_hi:[1,0,1]
	s_nop 0
	v_mov_b32_e32 v185, v109
	ds_read2_b64 v[108:111], v189 offset0:6 offset1:7
	v_pk_mul_f32 v[124:125], v[28:29], v[184:185]
	s_waitcnt lgkmcnt(1)
	v_pk_mul_f32 v[184:185], v[104:105], v[130:131] op_sel:[1,1] op_sel_hi:[0,1]
	v_pk_fma_f32 v[186:187], v[104:105], v[130:131], v[184:185] neg_lo:[0,0,1] neg_hi:[0,0,1]
	v_pk_fma_f32 v[104:105], v[104:105], v[130:131], v[184:185] op_sel_hi:[1,0,1]
	s_nop 0
	v_mov_b32_e32 v187, v105
	v_pk_mul_f32 v[104:105], v[106:107], v[132:133] op_sel:[1,1] op_sel_hi:[0,1]
	v_pk_fma_f32 v[184:185], v[106:107], v[132:133], v[104:105] neg_lo:[0,0,1] neg_hi:[0,0,1]
	v_pk_fma_f32 v[104:105], v[106:107], v[132:133], v[104:105] op_sel_hi:[1,0,1]
	v_pk_mul_f32 v[130:131], v[28:29], v[186:187]
	v_mov_b32_e32 v185, v105
	s_waitcnt lgkmcnt(0)
	v_pk_mul_f32 v[104:105], v[108:109], v[176:177] op_sel:[1,1] op_sel_hi:[0,1]
	v_pk_fma_f32 v[106:107], v[108:109], v[176:177], v[104:105] neg_lo:[0,0,1] neg_hi:[0,0,1]
	v_pk_fma_f32 v[104:105], v[108:109], v[176:177], v[104:105] op_sel_hi:[1,0,1]
	v_pk_mul_f32 v[108:109], v[110:111], v[180:181] op_sel:[1,1] op_sel_hi:[0,1]
	v_mov_b32_e32 v107, v105
	v_pk_mul_f32 v[176:177], v[28:29], v[106:107]
	ds_read2_b64 v[104:107], v189 offset0:8 offset1:9
	v_pk_mul_f32 v[132:133], v[28:29], v[184:185]
	v_pk_fma_f32 v[184:185], v[110:111], v[180:181], v[108:109] neg_lo:[0,0,1] neg_hi:[0,0,1]
	v_pk_fma_f32 v[108:109], v[110:111], v[180:181], v[108:109] op_sel_hi:[1,0,1]
	s_nop 0
	v_mov_b32_e32 v185, v109
	ds_read2_b64 v[108:111], v189 offset0:10 offset1:11
	v_pk_mul_f32 v[180:181], v[28:29], v[184:185]
	s_waitcnt lgkmcnt(1)
	v_pk_mul_f32 v[184:185], v[120:121], v[104:105] op_sel:[1,1] op_sel_hi:[1,0]
	s_nop 0
	v_pk_fma_f32 v[186:187], v[120:121], v[104:105], v[184:185] neg_lo:[0,0,1] neg_hi:[0,0,1]
	v_pk_fma_f32 v[104:105], v[120:121], v[104:105], v[184:185] op_sel_hi:[0,1,1]
	v_mov_b32_e32 v187, v105
	v_pk_mul_f32 v[104:105], v[106:107], v[122:123] op_sel:[1,1] op_sel_hi:[0,1]
	v_pk_fma_f32 v[184:185], v[106:107], v[122:123], v[104:105] neg_lo:[0,0,1] neg_hi:[0,0,1]
	v_pk_fma_f32 v[104:105], v[106:107], v[122:123], v[104:105] op_sel_hi:[1,0,1]
	v_pk_mul_f32 v[120:121], v[28:29], v[186:187]
	v_mov_b32_e32 v185, v105
	s_waitcnt lgkmcnt(0)
	v_pk_mul_f32 v[104:105], v[112:113], v[108:109] op_sel:[1,1] op_sel_hi:[1,0]
	v_pk_mul_f32 v[122:123], v[28:29], v[184:185]
	v_pk_fma_f32 v[106:107], v[112:113], v[108:109], v[104:105] neg_lo:[0,0,1] neg_hi:[0,0,1]
	v_pk_fma_f32 v[104:105], v[112:113], v[108:109], v[104:105] op_sel_hi:[0,1,1]
	v_mov_b32_e32 v107, v105
	v_pk_mul_f32 v[112:113], v[28:29], v[106:107]
	v_pk_mul_f32 v[108:109], v[178:179], v[110:111] op_sel:[1,1] op_sel_hi:[1,0]
	ds_read2_b64 v[104:107], v189 offset0:12 offset1:13
	v_pk_fma_f32 v[184:185], v[178:179], v[110:111], v[108:109] neg_lo:[0,0,1] neg_hi:[0,0,1]
	v_pk_fma_f32 v[108:109], v[178:179], v[110:111], v[108:109] op_sel_hi:[0,1,1]
	v_mov_b32_e32 v185, v109
	ds_read2_b64 v[108:111], v189 offset0:14 offset1:15
	v_pk_mul_f32 v[178:179], v[28:29], v[184:185]
	s_waitcnt lgkmcnt(1)
	v_pk_mul_f32 v[184:185], v[116:117], v[104:105] op_sel:[1,1] op_sel_hi:[1,0]
	s_nop 0
	v_pk_fma_f32 v[186:187], v[116:117], v[104:105], v[184:185] neg_lo:[0,0,1] neg_hi:[0,0,1]
	v_pk_fma_f32 v[104:105], v[116:117], v[104:105], v[184:185] op_sel_hi:[0,1,1]
	v_pk_mul_f32 v[116:117], v[106:107], v[114:115] op_sel:[1,1] op_sel_hi:[0,1]
	v_pk_fma_f32 v[184:185], v[106:107], v[114:115], v[116:117] neg_lo:[0,0,1] neg_hi:[0,0,1]
	v_pk_fma_f32 v[106:107], v[106:107], v[114:115], v[116:117] op_sel_hi:[1,0,1]
	s_waitcnt lgkmcnt(0)
	v_pk_mul_f32 v[114:115], v[134:135], v[108:109] op_sel:[1,1] op_sel_hi:[1,0]
	v_mov_b32_e32 v187, v105
	v_pk_fma_f32 v[116:117], v[134:135], v[108:109], v[114:115] neg_lo:[0,0,1] neg_hi:[0,0,1]
	v_pk_fma_f32 v[108:109], v[134:135], v[108:109], v[114:115] op_sel_hi:[0,1,1]
	v_mov_b32_e32 v117, v109
	v_pk_mul_f32 v[114:115], v[182:183], v[110:111] op_sel:[1,1] op_sel_hi:[1,0]
	v_pk_mul_f32 v[108:109], v[28:29], v[116:117]
	v_pk_fma_f32 v[116:117], v[182:183], v[110:111], v[114:115] neg_lo:[0,0,1] neg_hi:[0,0,1]
	v_pk_fma_f32 v[110:111], v[182:183], v[110:111], v[114:115] op_sel_hi:[0,1,1]
	v_pk_mul_f32 v[104:105], v[28:29], v[186:187]
	v_mov_b32_e32 v185, v107
	v_mov_b32_e32 v117, v111
	v_pk_mul_f32 v[106:107], v[28:29], v[184:185]
	v_pk_mul_f32 v[110:111], v[28:29], v[116:117]
	ds_write2_b64 v188, v[118:119], v[128:129] offset1:1
	ds_write2_b64 v188, v[126:127], v[124:125] offset0:2 offset1:3
	ds_write2_b64 v188, v[130:131], v[132:133] offset0:4 offset1:5
	ds_write2_b64 v188, v[176:177], v[180:181] offset0:6 offset1:7
	ds_write2_b64 v188, v[120:121], v[122:123] offset0:8 offset1:9
	ds_write2_b64 v188, v[112:113], v[178:179] offset0:10 offset1:11
	ds_write2_b64 v188, v[104:105], v[106:107] offset0:12 offset1:13
	ds_write2_b64 v188, v[108:109], v[110:111] offset0:14 offset1:15
	v_mov_b32_e32 v104, v208
	s_waitcnt lgkmcnt(0)
	s_barrier
	s_nop 0
	v_lshlrev_b32_e32 v105, 4, v104
	v_ashrrev_i32_e32 v105, 1, v105
	v_lshlrev_b32_e32 v104, 7, v104
	v_add3_u32 v180, s35, v105, v104
	ds_read2_b64 v[104:107], v180 offset1:1
	ds_read2_b64 v[108:111], v180 offset0:2 offset1:3
	ds_read2_b64 v[112:115], v180 offset0:8 offset1:9
	ds_read2_b64 v[116:119], v180 offset0:4 offset1:5
	ds_read2_b64 v[120:123], v180 offset0:6 offset1:7
	ds_read2_b64 v[124:127], v180 offset0:12 offset1:13
	ds_read2_b64 v[128:131], v180 offset0:10 offset1:11
	ds_read2_b64 v[132:135], v180 offset0:14 offset1:15
	s_waitcnt lgkmcnt(5)
	v_pk_add_f32 v[176:177], v[104:105], v[112:113]
	v_pk_add_f32 v[104:105], v[104:105], v[112:113] neg_lo:[0,1] neg_hi:[0,1]
	s_waitcnt lgkmcnt(2)
	v_pk_add_f32 v[112:113], v[116:117], v[124:125]
	v_pk_add_f32 v[116:117], v[116:117], v[124:125] neg_lo:[0,1] neg_hi:[0,1]
	s_nop 0
	v_xor_b32_e32 v124, 0x80000000, v117
	v_mov_b32_e32 v125, v116
	v_pk_add_f32 v[116:117], v[176:177], v[112:113]
	v_pk_add_f32 v[112:113], v[176:177], v[112:113] neg_lo:[0,1] neg_hi:[0,1]
	v_pk_add_f32 v[176:177], v[104:105], v[124:125]
	v_pk_add_f32 v[104:105], v[104:105], v[124:125] neg_lo:[0,1] neg_hi:[0,1]
	v_pk_add_f32 v[124:125], v[106:107], v[114:115]
	v_pk_add_f32 v[106:107], v[106:107], v[114:115] neg_lo:[0,1] neg_hi:[0,1]
	v_pk_add_f32 v[114:115], v[118:119], v[126:127]
	v_pk_add_f32 v[118:119], v[118:119], v[126:127] neg_lo:[0,1] neg_hi:[0,1]
	s_nop 0
	v_xor_b32_e32 v126, 0x80000000, v119
	v_mov_b32_e32 v127, v118
	v_pk_add_f32 v[118:119], v[124:125], v[114:115]
	v_pk_add_f32 v[114:115], v[124:125], v[114:115] neg_lo:[0,1] neg_hi:[0,1]
	v_pk_add_f32 v[124:125], v[106:107], v[126:127]
	v_pk_add_f32 v[106:107], v[106:107], v[126:127] neg_lo:[0,1] neg_hi:[0,1]
	s_waitcnt lgkmcnt(1)
	v_pk_add_f32 v[126:127], v[108:109], v[128:129]
	v_pk_add_f32 v[108:109], v[108:109], v[128:129] neg_lo:[0,1] neg_hi:[0,1]
	s_waitcnt lgkmcnt(0)
	v_pk_add_f32 v[128:129], v[120:121], v[132:133]
	v_pk_add_f32 v[120:121], v[120:121], v[132:133] neg_lo:[0,1] neg_hi:[0,1]
	s_nop 0
	v_xor_b32_e32 v132, 0x80000000, v121
	v_mov_b32_e32 v133, v120
	v_pk_add_f32 v[120:121], v[126:127], v[128:129]
	v_pk_add_f32 v[126:127], v[126:127], v[128:129] neg_lo:[0,1] neg_hi:[0,1]
	v_pk_add_f32 v[128:129], v[108:109], v[132:133]
	v_pk_add_f32 v[108:109], v[108:109], v[132:133] neg_lo:[0,1] neg_hi:[0,1]
	v_pk_add_f32 v[132:133], v[110:111], v[130:131]
	v_pk_add_f32 v[110:111], v[110:111], v[130:131] neg_lo:[0,1] neg_hi:[0,1]
	v_pk_add_f32 v[130:131], v[122:123], v[134:135]
	v_pk_add_f32 v[122:123], v[122:123], v[134:135] neg_lo:[0,1] neg_hi:[0,1]
	s_nop 0
	v_xor_b32_e32 v134, 0x80000000, v123
	v_mov_b32_e32 v135, v122
	v_pk_add_f32 v[122:123], v[132:133], v[130:131]
	v_pk_add_f32 v[130:131], v[132:133], v[130:131] neg_lo:[0,1] neg_hi:[0,1]
	v_pk_add_f32 v[132:133], v[110:111], v[134:135]
	v_pk_add_f32 v[110:111], v[110:111], v[134:135] neg_lo:[0,1] neg_hi:[0,1]
	v_pk_mul_f32 v[134:135], v[124:125], s[30:31] op_sel_hi:[1,0]
	s_nop 0
	v_pk_fma_f32 v[178:179], v[124:125], s[22:23], v[134:135] op_sel:[0,0,1] op_sel_hi:[1,0,0] neg_lo:[0,0,1] neg_hi:[0,0,1]
	v_pk_fma_f32 v[124:125], v[124:125], s[22:23], v[134:135] op_sel:[0,0,1] op_sel_hi:[1,0,0]
	s_nop 0
	v_mov_b32_e32 v179, v125
	v_pk_mul_f32 v[124:125], v[114:115], s[24:25] op_sel_hi:[1,0]
	s_nop 0
	v_pk_fma_f32 v[134:135], v[114:115], s[24:25], v[124:125] op_sel:[0,0,1] op_sel_hi:[1,0,0] neg_lo:[0,0,1] neg_hi:[0,0,1]
	v_pk_fma_f32 v[114:115], v[114:115], s[24:25], v[124:125] op_sel_hi:[1,0,0]
	s_nop 0
	v_mov_b32_e32 v135, v115
	v_pk_mul_f32 v[114:115], v[106:107], s[22:23] op_sel_hi:[1,0]
	s_nop 0
	v_pk_fma_f32 v[124:125], v[106:107], s[30:31], v[114:115] op_sel:[0,0,1] op_sel_hi:[1,0,0] neg_lo:[0,0,1] neg_hi:[0,0,1]
	v_pk_fma_f32 v[106:107], v[106:107], s[30:31], v[114:115] op_sel:[0,0,1] op_sel_hi:[1,0,0]
	s_nop 0
	v_mov_b32_e32 v125, v107
	v_pk_mul_f32 v[106:107], v[128:129], s[24:25] op_sel_hi:[1,0]
	s_nop 0
	v_pk_fma_f32 v[114:115], v[128:129], s[24:25], v[106:107] op_sel:[0,0,1] op_sel_hi:[1,0,0] neg_lo:[0,0,1] neg_hi:[0,0,1]
	v_pk_fma_f32 v[106:107], v[128:129], s[24:25], v[106:107] op_sel_hi:[1,0,0]
	s_nop 0
	v_mov_b32_e32 v115, v107
	v_mov_b32_e32 v107, v126
	v_mul_f32_e32 v126, 0x3f3504f3, v109
	v_xor_b32_e32 v106, 0x80000000, v127
	v_pk_fma_f32 v[108:109], v[108:109], s[18:19], v[126:127] op_sel_hi:[0,1,0] neg_lo:[0,0,1] neg_hi:[0,0,1]
	v_pk_mul_f32 v[126:127], v[132:133], s[22:23] op_sel_hi:[1,0]
	s_nop 0
	v_pk_fma_f32 v[128:129], v[132:133], s[30:31], v[126:127] op_sel:[0,0,1] op_sel_hi:[1,0,0] neg_lo:[0,0,1] neg_hi:[0,0,1]
	v_pk_fma_f32 v[126:127], v[132:133], s[30:31], v[126:127] op_sel:[0,0,1] op_sel_hi:[1,0,0]
	s_nop 0
	v_mul_f32_e32 v126, 0x3f3504f3, v131
	v_mov_b32_e32 v129, v127
	v_pk_fma_f32 v[126:127], v[130:131], s[18:19], v[126:127] op_sel_hi:[0,1,0] neg_lo:[0,0,1] neg_hi:[0,0,1]
	v_pk_mul_f32 v[130:131], v[110:111], s[88:89]
	v_pk_add_f32 v[132:133], v[178:179], v[128:129]
	v_pk_fma_f32 v[110:111], v[110:111], s[22:23], v[130:131] op_sel:[0,0,1] op_sel_hi:[1,0,0] neg_lo:[1,0,0] neg_hi:[1,0,0]
	v_pk_add_f32 v[130:131], v[116:117], v[120:121]
	v_pk_add_f32 v[116:117], v[116:117], v[120:121] neg_lo:[0,1] neg_hi:[0,1]
	v_pk_add_f32 v[120:121], v[118:119], v[122:123]
	v_pk_add_f32 v[118:119], v[118:119], v[122:123] neg_lo:[0,1] neg_hi:[0,1]
	v_pk_add_f32 v[128:129], v[178:179], v[128:129] neg_lo:[0,1] neg_hi:[0,1]
	v_xor_b32_e32 v122, 0x80000000, v119
	v_mov_b32_e32 v123, v118
	v_pk_add_f32 v[118:119], v[130:131], v[120:121]
	v_pk_add_f32 v[120:121], v[130:131], v[120:121] neg_lo:[0,1] neg_hi:[0,1]
	v_pk_add_f32 v[130:131], v[116:117], v[122:123]
	v_pk_add_f32 v[116:117], v[116:117], v[122:123] neg_lo:[0,1] neg_hi:[0,1]
	v_pk_add_f32 v[122:123], v[176:177], v[114:115]
	v_pk_add_f32 v[114:115], v[176:177], v[114:115] neg_lo:[0,1] neg_hi:[0,1]
	v_xor_b32_e32 v176, 0x80000000, v129
	v_mov_b32_e32 v177, v128
	v_pk_add_f32 v[128:129], v[122:123], v[132:133]
	v_pk_add_f32 v[122:123], v[122:123], v[132:133] neg_lo:[0,1] neg_hi:[0,1]
	v_pk_add_f32 v[132:133], v[114:115], v[176:177]
	v_pk_add_f32 v[114:115], v[114:115], v[176:177] neg_lo:[0,1] neg_hi:[0,1]
	v_pk_add_f32 v[176:177], v[112:113], v[106:107]
	v_pk_add_f32 v[106:107], v[112:113], v[106:107] neg_lo:[0,1] neg_hi:[0,1]
	v_pk_add_f32 v[112:113], v[134:135], v[126:127]
	v_pk_add_f32 v[126:127], v[134:135], v[126:127] neg_lo:[0,1] neg_hi:[0,1]
	s_nop 0
	v_xor_b32_e32 v134, 0x80000000, v127
	v_mov_b32_e32 v135, v126
	v_pk_add_f32 v[126:127], v[176:177], v[112:113]
	v_pk_add_f32 v[112:113], v[176:177], v[112:113] neg_lo:[0,1] neg_hi:[0,1]
	v_pk_add_f32 v[176:177], v[106:107], v[134:135]
	v_pk_add_f32 v[106:107], v[106:107], v[134:135] neg_lo:[0,1] neg_hi:[0,1]
	v_pk_add_f32 v[134:135], v[104:105], v[108:109]
	v_pk_add_f32 v[104:105], v[104:105], v[108:109] neg_lo:[0,1] neg_hi:[0,1]
	v_pk_add_f32 v[108:109], v[124:125], v[110:111]
	v_pk_add_f32 v[110:111], v[124:125], v[110:111] neg_lo:[0,1] neg_hi:[0,1]
	s_nop 0
	v_xor_b32_e32 v124, 0x80000000, v111
	v_mov_b32_e32 v125, v110
	v_pk_add_f32 v[110:111], v[134:135], v[108:109]
	v_pk_add_f32 v[108:109], v[134:135], v[108:109] neg_lo:[0,1] neg_hi:[0,1]
	v_pk_add_f32 v[134:135], v[104:105], v[124:125]
	v_pk_add_f32 v[104:105], v[104:105], v[124:125] neg_lo:[0,1] neg_hi:[0,1]
	ds_write2_b64 v180, v[118:119], v[128:129] offset1:1
	ds_write2_b64 v180, v[126:127], v[110:111] offset0:2 offset1:3
	ds_write2_b64 v180, v[130:131], v[132:133] offset0:4 offset1:5
	ds_write2_b64 v180, v[176:177], v[134:135] offset0:6 offset1:7
	ds_write2_b64 v180, v[120:121], v[122:123] offset0:8 offset1:9
	ds_write2_b64 v180, v[112:113], v[108:109] offset0:10 offset1:11
	ds_write2_b64 v180, v[116:117], v[114:115] offset0:12 offset1:13
	ds_write2_b64 v180, v[106:107], v[104:105] offset0:14 offset1:15
	v_mov_b32_e32 v104, v208
	s_waitcnt lgkmcnt(0)
	s_nop 0
	v_and_b32_e32 v128, 15, v104
	v_lshlrev_b32_e32 v106, 3, v128
	v_cvt_f32_ubyte0_e32 v128, v128
	v_mul_f32_e32 v205, 0x3b800000, v128
	v_mul_f32_e32 v128, 0x41400000, v205
	v_sin_f32_e32 v176, v128
	v_sin_f32_e32 v178, v205
	v_cos_f32_e32 v177, v128
	v_cos_f32_e32 v180, v205
	v_lshlrev_b32_e32 v104, 4, v104
	v_and_b32_e32 v104, 0xffffff00, v104
	v_pk_mul_f32 v[182:183], v[178:179], v[176:177] op_sel_hi:[0,1]
	v_ashrrev_i32_e32 v105, 1, v104
	v_pk_fma_f32 v[184:185], v[180:181], v[176:177], v[182:183] op_sel:[0,0,1] op_sel_hi:[0,1,0]
	v_pk_fma_f32 v[182:183], v[180:181], v[176:177], v[182:183] op_sel:[0,0,1] op_sel_hi:[0,1,0] neg_lo:[0,0,1] neg_hi:[0,0,1]
	v_add_u32_e32 v105, s35, v105
	v_lshlrev_b32_e32 v104, 3, v104
	v_pk_mov_b32 v[188:189], v[182:183], v[184:185] op_sel:[1,0]
	v_add3_u32 v204, v105, v104, v106
	v_mov_b32_e32 v186, v184
	v_mov_b32_e32 v187, v183
	v_pk_mul_f32 v[188:189], v[178:179], v[188:189] op_sel_hi:[0,1]
	v_mov_b32_e32 v179, v180
	ds_read2_b64 v[104:107], v204 offset1:17
	ds_read2_b64 v[108:111], v204 offset0:34 offset1:51
	ds_read2_b64 v[112:115], v204 offset0:68 offset1:85
	ds_read2_b64 v[116:119], v204 offset0:102 offset1:119
	ds_read2_b64 v[120:123], v204 offset0:136 offset1:153
	ds_read2_b64 v[124:127], v204 offset0:170 offset1:187
	v_pk_fma_f32 v[190:191], v[180:181], v[186:187], v[188:189] op_sel_hi:[0,1,1]
	v_pk_fma_f32 v[186:187], v[180:181], v[186:187], v[188:189] op_sel_hi:[0,1,1] neg_lo:[0,0,1] neg_hi:[0,0,1]
	v_mov_b32_e32 v181, v178
	s_waitcnt lgkmcnt(5)
	v_pk_mul_f32 v[194:195], v[106:107], v[178:179] op_sel_hi:[1,0]
	ds_read2_b64 v[128:131], v204 offset0:204 offset1:221
	ds_read2_b64 v[132:135], v204 offset0:238 offset1:255
	v_pk_fma_f32 v[196:197], v[106:107], v[180:181], v[194:195] op_sel:[0,0,1] op_sel_hi:[1,1,0] neg_lo:[0,0,1] neg_hi:[0,0,1]
	v_pk_fma_f32 v[106:107], v[106:107], v[180:181], v[194:195] op_sel:[0,0,1] op_sel_hi:[1,0,0]
	v_mov_b32_e32 v188, v190
	v_mov_b32_e32 v197, v107
	v_pk_mul_f32 v[106:107], v[178:179], v[178:179] op_sel:[0,1] op_sel_hi:[0,0]
	v_pk_fma_f32 v[194:195], v[180:181], v[178:179], v[106:107] op_sel_hi:[0,1,1]
	v_pk_fma_f32 v[106:107], v[180:181], v[178:179], v[106:107] op_sel_hi:[0,1,1] neg_lo:[0,0,1] neg_hi:[0,0,1]
	v_mov_b32_e32 v198, v194
	v_mov_b32_e32 v199, v107
	s_waitcnt lgkmcnt(6)
	v_pk_mul_f32 v[194:195], v[108:109], v[194:195] op_sel:[1,0] op_sel_hi:[0,0]
	v_pk_fma_f32 v[200:201], v[108:109], v[106:107], v[194:195] op_sel:[0,1,0] neg_lo:[0,0,1] neg_hi:[0,0,1]
	v_pk_fma_f32 v[106:107], v[108:109], v[106:107], v[194:195] op_sel:[0,1,0]
	v_pk_mul_f32 v[108:109], v[178:179], v[198:199] op_sel:[1,0] op_sel_hi:[0,1]
	v_mov_b32_e32 v201, v107
	v_pk_mul_f32 v[106:107], v[178:179], v[198:199]
	v_pk_add_f32 v[108:109], v[108:109], v[108:109] op_sel:[0,1] op_sel_hi:[0,1]
	v_pk_mul_f32 v[108:109], v[110:111], v[108:109] op_sel:[1,0] op_sel_hi:[0,1]
	v_pk_add_f32 v[106:107], v[106:107], v[106:107] op_sel:[1,0] op_sel_hi:[1,0] neg_lo:[0,1] neg_hi:[0,1]
	v_mov_b32_e32 v189, v187
	v_pk_fma_f32 v[194:195], v[110:111], v[106:107], v[108:109] neg_lo:[0,0,1] neg_hi:[0,0,1]
	v_pk_fma_f32 v[106:107], v[110:111], v[106:107], v[108:109]
	v_mul_f32_e32 v195, 4.0, v205
	v_sin_f32_e32 v198, v195
	v_cos_f32_e32 v202, v195
	v_mov_b32_e32 v195, v107
	v_pk_mul_f32 v[192:193], v[180:181], v[188:189]
	s_waitcnt lgkmcnt(5)
	v_pk_mul_f32 v[106:107], v[198:199], v[112:113] op_sel:[0,1] op_sel_hi:[0,0]
	v_pk_fma_f32 v[108:109], v[202:203], v[112:113], v[106:107] neg_lo:[0,0,1] neg_hi:[0,0,1]
	v_pk_fma_f32 v[106:107], v[202:203], v[112:113], v[106:107] op_sel_hi:[0,1,1]
	v_mov_b32_e32 v199, v202
	v_mov_b32_e32 v109, v107
	v_pk_mul_f32 v[106:107], v[178:179], v[198:199] op_sel_hi:[0,1]
	v_pk_fma_f32 v[110:111], v[180:181], v[198:199], v[106:107] op_sel:[0,0,1] op_sel_hi:[0,1,0]
	v_pk_fma_f32 v[106:107], v[180:181], v[198:199], v[106:107] op_sel:[0,0,1] op_sel_hi:[0,1,0] neg_lo:[0,0,1] neg_hi:[0,0,1]
	v_pk_mul_f32 v[198:199], v[110:111], v[114:115] op_sel:[0,1] op_sel_hi:[0,0]
	v_mov_b32_e32 v112, v110
	v_mov_b32_e32 v113, v107
	v_pk_mov_b32 v[110:111], v[106:107], v[110:111] op_sel:[1,0]
	v_pk_fma_f32 v[202:203], v[106:107], v[114:115], v[198:199] op_sel:[1,0,0] neg_lo:[0,0,1] neg_hi:[0,0,1]
	v_pk_fma_f32 v[106:107], v[106:107], v[114:115], v[198:199] op_sel:[1,0,0]
	v_pk_mul_f32 v[188:189], v[178:179], v[188:189]
	v_mov_b32_e32 v203, v107
	v_pk_mul_f32 v[106:107], v[178:179], v[110:111] op_sel_hi:[0,1]
	v_pk_fma_f32 v[110:111], v[180:181], v[112:113], v[106:107] op_sel_hi:[0,1,1]
	v_pk_fma_f32 v[106:107], v[180:181], v[112:113], v[106:107] op_sel_hi:[0,1,1] neg_lo:[0,0,1] neg_hi:[0,0,1]
	v_mov_b32_e32 v112, v110
	v_mov_b32_e32 v113, v107
	s_waitcnt lgkmcnt(4)
	v_pk_mul_f32 v[110:111], v[116:117], v[110:111] op_sel:[1,0] op_sel_hi:[0,0]
	v_pk_fma_f32 v[114:115], v[116:117], v[106:107], v[110:111] op_sel:[0,1,0] neg_lo:[0,0,1] neg_hi:[0,0,1]
	v_pk_fma_f32 v[106:107], v[116:117], v[106:107], v[110:111] op_sel:[0,1,0]
	v_pk_mul_f32 v[110:111], v[180:181], v[112:113]
	v_mov_b32_e32 v115, v107
	v_pk_mul_f32 v[106:107], v[178:179], v[112:113]
	v_pk_add_f32 v[110:111], v[110:111], v[110:111] op_sel:[0,1] op_sel_hi:[0,1]
	v_pk_mul_f32 v[110:111], v[118:119], v[110:111] op_sel:[1,0] op_sel_hi:[0,1]
	v_pk_add_f32 v[106:107], v[106:107], v[106:107] op_sel:[1,0] op_sel_hi:[1,0] neg_lo:[0,1] neg_hi:[0,1]
	s_nop 0
	v_pk_fma_f32 v[112:113], v[118:119], v[106:107], v[110:111] neg_lo:[0,0,1] neg_hi:[0,0,1]
	v_pk_fma_f32 v[106:107], v[118:119], v[106:107], v[110:111]
	v_mul_f32_e32 v113, 0x41000000, v205
	v_sin_f32_e32 v116, v113
	v_cos_f32_e32 v198, v113
	v_mov_b32_e32 v113, v107
	s_waitcnt lgkmcnt(3)
	v_pk_mul_f32 v[106:107], v[116:117], v[120:121] op_sel:[0,1] op_sel_hi:[0,0]
	v_pk_fma_f32 v[110:111], v[198:199], v[120:121], v[106:107] neg_lo:[0,0,1] neg_hi:[0,0,1]
	v_pk_fma_f32 v[106:107], v[198:199], v[120:121], v[106:107] op_sel_hi:[0,1,1]
	v_mov_b32_e32 v117, v198
	v_mov_b32_e32 v111, v107
	v_pk_mul_f32 v[106:107], v[178:179], v[116:117] op_sel_hi:[0,1]
	v_pk_fma_f32 v[118:119], v[180:181], v[116:117], v[106:107] op_sel:[0,0,1] op_sel_hi:[0,1,0]
	v_pk_fma_f32 v[106:107], v[180:181], v[116:117], v[106:107] op_sel:[0,0,1] op_sel_hi:[0,1,0] neg_lo:[0,0,1] neg_hi:[0,0,1]
	v_pk_mul_f32 v[120:121], v[118:119], v[122:123] op_sel:[0,1] op_sel_hi:[0,0]
	v_mov_b32_e32 v116, v118
	v_mov_b32_e32 v117, v107
	v_pk_mov_b32 v[118:119], v[106:107], v[118:119] op_sel:[1,0]
	v_pk_fma_f32 v[198:199], v[106:107], v[122:123], v[120:121] op_sel:[1,0,0] neg_lo:[0,0,1] neg_hi:[0,0,1]
	v_pk_fma_f32 v[106:107], v[106:107], v[122:123], v[120:121] op_sel:[1,0,0]
	v_mov_b32_e32 v122, v177
	v_mov_b32_e32 v199, v107
	v_pk_mul_f32 v[106:107], v[178:179], v[118:119] op_sel_hi:[0,1]
	v_pk_fma_f32 v[118:119], v[180:181], v[116:117], v[106:107] op_sel_hi:[0,1,1]
	v_pk_fma_f32 v[106:107], v[180:181], v[116:117], v[106:107] op_sel_hi:[0,1,1] neg_lo:[0,0,1] neg_hi:[0,0,1]
	v_mov_b32_e32 v116, v118
	s_waitcnt lgkmcnt(2)
	v_pk_mul_f32 v[118:119], v[118:119], v[124:125] op_sel:[0,1] op_sel_hi:[0,0]
	v_mov_b32_e32 v117, v107
	v_pk_fma_f32 v[120:121], v[106:107], v[124:125], v[118:119] op_sel:[1,0,0] neg_lo:[0,0,1] neg_hi:[0,0,1]
	v_pk_fma_f32 v[106:107], v[106:107], v[124:125], v[118:119] op_sel:[1,0,0]
	s_nop 0
	v_mov_b32_e32 v121, v107
	v_pk_mul_f32 v[106:107], v[178:179], v[116:117]
	v_pk_mul_f32 v[116:117], v[180:181], v[116:117]
	v_pk_add_f32 v[106:107], v[106:107], v[106:107] op_sel:[1,0] op_sel_hi:[1,0] neg_lo:[0,1] neg_hi:[0,1]
	v_pk_add_f32 v[116:117], v[116:117], v[116:117] op_sel:[0,1] op_sel_hi:[0,1]
	v_pk_mul_f32 v[116:117], v[116:117], v[126:127] op_sel:[0,1] op_sel_hi:[1,0]
	s_nop 0
	v_pk_fma_f32 v[118:119], v[106:107], v[126:127], v[116:117] neg_lo:[0,0,1] neg_hi:[0,0,1]
	v_pk_fma_f32 v[106:107], v[106:107], v[126:127], v[116:117]
	v_mov_b32_e32 v116, v177
	v_mov_b32_e32 v119, v107
	s_waitcnt lgkmcnt(1)
	v_pk_mul_f32 v[106:107], v[176:177], v[128:129] op_sel:[0,1] op_sel_hi:[0,0]
	v_pk_fma_f32 v[116:117], v[116:117], v[128:129], v[106:107] neg_lo:[0,0,1] neg_hi:[0,0,1]
	v_pk_fma_f32 v[106:107], v[122:123], v[128:129], v[106:107] op_sel_hi:[0,1,1]
	v_mov_b32_e32 v117, v107
	v_pk_mul_f32 v[106:107], v[184:185], v[130:131] op_sel:[0,1] op_sel_hi:[0,0]
	v_pk_fma_f32 v[122:123], v[182:183], v[130:131], v[106:107] op_sel:[1,0,0] neg_lo:[0,0,1] neg_hi:[0,0,1]
	v_pk_fma_f32 v[106:107], v[182:183], v[130:131], v[106:107] op_sel:[1,0,0]
	v_pk_add_f32 v[126:127], v[192:193], v[192:193] op_sel:[0,1] op_sel_hi:[0,1]
	v_mov_b32_e32 v123, v107
	s_waitcnt lgkmcnt(0)
	v_pk_mul_f32 v[106:107], v[190:191], v[132:133] op_sel:[0,1] op_sel_hi:[0,0]
	v_pk_fma_f32 v[124:125], v[186:187], v[132:133], v[106:107] op_sel:[1,0,0] neg_lo:[0,0,1] neg_hi:[0,0,1]
	v_pk_fma_f32 v[106:107], v[186:187], v[132:133], v[106:107] op_sel:[1,0,0]
	v_pk_mul_f32 v[126:127], v[126:127], v[134:135] op_sel:[0,1] op_sel_hi:[1,0]
	v_mov_b32_e32 v125, v107
	v_pk_add_f32 v[106:107], v[188:189], v[188:189] op_sel:[1,0] op_sel_hi:[1,0] neg_lo:[0,1] neg_hi:[0,1]
	v_pk_add_f32 v[130:131], v[202:203], v[122:123]
	v_pk_fma_f32 v[128:129], v[106:107], v[134:135], v[126:127] neg_lo:[0,0,1] neg_hi:[0,0,1]
	v_pk_fma_f32 v[106:107], v[106:107], v[134:135], v[126:127]
	v_pk_add_f32 v[122:123], v[202:203], v[122:123] neg_lo:[0,1] neg_hi:[0,1]
	v_mov_b32_e32 v129, v107
	v_pk_add_f32 v[106:107], v[104:105], v[110:111]
	v_pk_add_f32 v[104:105], v[104:105], v[110:111] neg_lo:[0,1] neg_hi:[0,1]
	v_pk_add_f32 v[110:111], v[108:109], v[116:117]
	v_pk_add_f32 v[108:109], v[108:109], v[116:117] neg_lo:[0,1] neg_hi:[0,1]
	v_pk_add_f32 v[126:127], v[196:197], v[198:199] neg_lo:[0,1] neg_hi:[0,1]
	v_xor_b32_e32 v116, 0x80000000, v109
	v_mov_b32_e32 v117, v108
	v_pk_add_f32 v[108:109], v[106:107], v[110:111]
	v_pk_add_f32 v[106:107], v[106:107], v[110:111] neg_lo:[0,1] neg_hi:[0,1]
	v_pk_add_f32 v[110:111], v[104:105], v[116:117]
	v_pk_add_f32 v[104:105], v[104:105], v[116:117] neg_lo:[0,1] neg_hi:[0,1]
	v_pk_add_f32 v[116:117], v[196:197], v[198:199]
	v_xor_b32_e32 v132, 0x80000000, v123
	v_mov_b32_e32 v133, v122
	v_pk_add_f32 v[134:135], v[114:115], v[124:125]
	v_pk_add_f32 v[114:115], v[114:115], v[124:125] neg_lo:[0,1] neg_hi:[0,1]
	v_pk_add_f32 v[122:123], v[116:117], v[130:131]
	v_pk_add_f32 v[116:117], v[116:117], v[130:131] neg_lo:[0,1] neg_hi:[0,1]
	v_pk_add_f32 v[130:131], v[126:127], v[132:133]
	v_pk_add_f32 v[126:127], v[126:127], v[132:133] neg_lo:[0,1] neg_hi:[0,1]
	v_pk_add_f32 v[132:133], v[200:201], v[120:121]
	v_pk_add_f32 v[120:121], v[200:201], v[120:121] neg_lo:[0,1] neg_hi:[0,1]
	v_xor_b32_e32 v124, 0x80000000, v115
	v_mov_b32_e32 v125, v114
	v_pk_add_f32 v[176:177], v[112:113], v[128:129]
	v_pk_add_f32 v[112:113], v[112:113], v[128:129] neg_lo:[0,1] neg_hi:[0,1]
	v_pk_add_f32 v[114:115], v[132:133], v[134:135]
	v_pk_add_f32 v[132:133], v[132:133], v[134:135] neg_lo:[0,1] neg_hi:[0,1]
	v_pk_add_f32 v[134:135], v[120:121], v[124:125]
	v_pk_add_f32 v[120:121], v[120:121], v[124:125] neg_lo:[0,1] neg_hi:[0,1]
	v_pk_add_f32 v[124:125], v[194:195], v[118:119]
	v_pk_add_f32 v[118:119], v[194:195], v[118:119] neg_lo:[0,1] neg_hi:[0,1]
	v_xor_b32_e32 v128, 0x80000000, v113
	v_mov_b32_e32 v129, v112
	v_pk_add_f32 v[112:113], v[124:125], v[176:177]
	v_pk_add_f32 v[124:125], v[124:125], v[176:177] neg_lo:[0,1] neg_hi:[0,1]
	v_pk_add_f32 v[176:177], v[118:119], v[128:129]
	v_pk_add_f32 v[118:119], v[118:119], v[128:129] neg_lo:[0,1] neg_hi:[0,1]
	v_pk_mul_f32 v[128:129], v[130:131], s[30:31] op_sel_hi:[1,0]
	s_nop 0
	v_pk_fma_f32 v[178:179], v[130:131], s[22:23], v[128:129] op_sel:[0,0,1] op_sel_hi:[1,0,0] neg_lo:[0,0,1] neg_hi:[0,0,1]
	v_pk_fma_f32 v[128:129], v[130:131], s[22:23], v[128:129] op_sel:[0,0,1] op_sel_hi:[1,0,0]
	s_nop 0
	v_mov_b32_e32 v179, v129
	v_pk_mul_f32 v[128:129], v[116:117], s[24:25] op_sel_hi:[1,0]
	s_nop 0
	v_pk_fma_f32 v[130:131], v[116:117], s[24:25], v[128:129] op_sel:[0,0,1] op_sel_hi:[1,0,0] neg_lo:[0,0,1] neg_hi:[0,0,1]
	v_pk_fma_f32 v[116:117], v[116:117], s[24:25], v[128:129] op_sel_hi:[1,0,0]
	s_nop 0
	v_mov_b32_e32 v131, v117
	v_pk_mul_f32 v[116:117], v[126:127], s[22:23] op_sel_hi:[1,0]
	s_nop 0
	v_pk_fma_f32 v[128:129], v[126:127], s[30:31], v[116:117] op_sel:[0,0,1] op_sel_hi:[1,0,0] neg_lo:[0,0,1] neg_hi:[0,0,1]
	v_pk_fma_f32 v[116:117], v[126:127], s[30:31], v[116:117] op_sel:[0,0,1] op_sel_hi:[1,0,0]
	s_nop 0
	v_mov_b32_e32 v129, v117
	v_pk_mul_f32 v[116:117], v[134:135], s[24:25] op_sel_hi:[1,0]
	s_nop 0
	v_pk_fma_f32 v[126:127], v[134:135], s[24:25], v[116:117] op_sel:[0,0,1] op_sel_hi:[1,0,0] neg_lo:[0,0,1] neg_hi:[0,0,1]
	v_pk_fma_f32 v[116:117], v[134:135], s[24:25], v[116:117] op_sel_hi:[1,0,0]
	s_nop 0
	v_mov_b32_e32 v127, v117
	v_mov_b32_e32 v117, v132
	v_mul_f32_e32 v132, 0x3f3504f3, v121
	v_xor_b32_e32 v116, 0x80000000, v133
	v_pk_fma_f32 v[120:121], v[120:121], s[18:19], v[132:133] op_sel_hi:[0,1,0] neg_lo:[0,0,1] neg_hi:[0,0,1]
	v_pk_mul_f32 v[132:133], v[176:177], s[22:23] op_sel_hi:[1,0]
	s_nop 0
	v_pk_fma_f32 v[134:135], v[176:177], s[30:31], v[132:133] op_sel:[0,0,1] op_sel_hi:[1,0,0] neg_lo:[0,0,1] neg_hi:[0,0,1]
	v_pk_fma_f32 v[132:133], v[176:177], s[30:31], v[132:133] op_sel:[0,0,1] op_sel_hi:[1,0,0]
	s_nop 0
	v_mul_f32_e32 v132, 0x3f3504f3, v125
	v_mov_b32_e32 v135, v133
	v_pk_fma_f32 v[124:125], v[124:125], s[18:19], v[132:133] op_sel_hi:[0,1,0] neg_lo:[0,0,1] neg_hi:[0,0,1]
	v_pk_mul_f32 v[132:133], v[118:119], s[88:89]
	s_nop 0
	v_pk_fma_f32 v[118:119], v[118:119], s[22:23], v[132:133] op_sel:[0,0,1] op_sel_hi:[1,0,0] neg_lo:[1,0,0] neg_hi:[1,0,0]
	v_pk_add_f32 v[132:133], v[108:109], v[114:115]
	v_pk_add_f32 v[108:109], v[108:109], v[114:115] neg_lo:[0,1] neg_hi:[0,1]
	v_pk_add_f32 v[114:115], v[122:123], v[112:113]
	v_pk_add_f32 v[112:113], v[122:123], v[112:113] neg_lo:[0,1] neg_hi:[0,1]
	s_nop 0
	v_xor_b32_e32 v122, 0x80000000, v113
	v_mov_b32_e32 v123, v112
	v_pk_add_f32 v[112:113], v[132:133], v[114:115]
	v_pk_add_f32 v[114:115], v[132:133], v[114:115] neg_lo:[0,1] neg_hi:[0,1]
	v_pk_add_f32 v[132:133], v[108:109], v[122:123]
	v_pk_add_f32 v[108:109], v[108:109], v[122:123] neg_lo:[0,1] neg_hi:[0,1]
	v_pk_add_f32 v[122:123], v[110:111], v[126:127]
	v_pk_add_f32 v[110:111], v[110:111], v[126:127] neg_lo:[0,1] neg_hi:[0,1]
	v_pk_add_f32 v[126:127], v[178:179], v[134:135]
	v_pk_add_f32 v[134:135], v[178:179], v[134:135] neg_lo:[0,1] neg_hi:[0,1]
	s_nop 0
	v_xor_b32_e32 v176, 0x80000000, v135
	v_mov_b32_e32 v177, v134
	v_pk_add_f32 v[134:135], v[122:123], v[126:127]
	v_pk_add_f32 v[122:123], v[122:123], v[126:127] neg_lo:[0,1] neg_hi:[0,1]
	v_pk_add_f32 v[126:127], v[110:111], v[176:177]
	v_pk_add_f32 v[110:111], v[110:111], v[176:177] neg_lo:[0,1] neg_hi:[0,1]
	v_pk_add_f32 v[176:177], v[106:107], v[116:117]
	v_pk_add_f32 v[106:107], v[106:107], v[116:117] neg_lo:[0,1] neg_hi:[0,1]
	v_pk_add_f32 v[116:117], v[130:131], v[124:125]
	v_pk_add_f32 v[124:125], v[130:131], v[124:125] neg_lo:[0,1] neg_hi:[0,1]
	s_nop 0
	v_xor_b32_e32 v130, 0x80000000, v125
	v_mov_b32_e32 v131, v124
	v_pk_add_f32 v[124:125], v[176:177], v[116:117]
	v_pk_add_f32 v[116:117], v[176:177], v[116:117] neg_lo:[0,1] neg_hi:[0,1]
	v_pk_add_f32 v[176:177], v[106:107], v[130:131]
	v_pk_add_f32 v[106:107], v[106:107], v[130:131] neg_lo:[0,1] neg_hi:[0,1]
	v_pk_add_f32 v[130:131], v[104:105], v[120:121]
	v_pk_add_f32 v[104:105], v[104:105], v[120:121] neg_lo:[0,1] neg_hi:[0,1]
	v_pk_add_f32 v[120:121], v[128:129], v[118:119]
	v_pk_add_f32 v[118:119], v[128:129], v[118:119] neg_lo:[0,1] neg_hi:[0,1]
	s_nop 0
	v_xor_b32_e32 v128, 0x80000000, v119
	v_mov_b32_e32 v129, v118
	v_pk_add_f32 v[118:119], v[130:131], v[120:121]
	v_pk_add_f32 v[120:121], v[130:131], v[120:121] neg_lo:[0,1] neg_hi:[0,1]
	v_pk_add_f32 v[130:131], v[104:105], v[128:129]
	v_pk_add_f32 v[104:105], v[104:105], v[128:129] neg_lo:[0,1] neg_hi:[0,1]
	v_mov_b32_e32 v128, v208
	ds_write2_b64 v204, v[112:113], v[134:135] offset1:17
	ds_write2_b64 v204, v[124:125], v[118:119] offset0:34 offset1:51
	ds_write2_b64 v204, v[132:133], v[126:127] offset0:68 offset1:85
	ds_write2_b64 v204, v[176:177], v[130:131] offset0:102 offset1:119
	ds_write2_b64 v204, v[114:115], v[122:123] offset0:136 offset1:153
	ds_write2_b64 v204, v[116:117], v[120:121] offset0:170 offset1:187
	ds_write2_b64 v204, v[108:109], v[110:111] offset0:204 offset1:221
	ds_write2_b64 v204, v[106:107], v[104:105] offset0:238 offset1:255
	s_waitcnt lgkmcnt(0)
	s_barrier
	s_nop 0
	v_and_b32_e32 v104, 0xff, v128
	v_lshlrev_b32_e32 v105, 4, v128
	v_cvt_f32_ubyte0_e32 v128, v128
	v_mul_f32_e32 v205, 0x39800000, v128
	v_mul_f32_e32 v129, 0x41400000, v205
	v_sin_f32_e32 v130, v129
	v_sin_f32_e32 v132, v205
	v_cos_f32_e32 v131, v129
	v_cos_f32_e32 v128, v205
	v_and_or_b32 v104, v105, s93, v104
	v_ashrrev_i32_e32 v105, 4, v104
	v_pk_mul_f32 v[182:183], v[132:133], v[130:131] op_sel_hi:[0,1]
	v_pk_fma_f32 v[184:185], v[128:129], v[130:131], v[182:183] op_sel:[0,0,1] op_sel_hi:[0,1,0]
	v_pk_fma_f32 v[182:183], v[128:129], v[130:131], v[182:183] op_sel:[0,0,1] op_sel_hi:[0,1,0] neg_lo:[0,0,1] neg_hi:[0,0,1]
	v_lshlrev_b32_e32 v105, 3, v105
	v_lshlrev_b32_e32 v104, 3, v104
	v_pk_mov_b32 v[188:189], v[182:183], v[184:185] op_sel:[1,0]
	v_add3_u32 v204, s35, v105, v104
	v_mov_b32_e32 v186, v184
	v_mov_b32_e32 v187, v183
	v_pk_mul_f32 v[188:189], v[132:133], v[188:189] op_sel_hi:[0,1]
	v_mov_b32_e32 v133, v128
	ds_read_b64 v[104:105], v204
	ds_read_b64 v[106:107], v204 offset:2176
	ds_read_b64 v[108:109], v204 offset:4352
	ds_read_b64 v[110:111], v204 offset:6528
	ds_read_b64 v[112:113], v204 offset:8704
	ds_read_b64 v[114:115], v204 offset:10880
	ds_read_b64 v[116:117], v204 offset:13056
	ds_read_b64 v[118:119], v204 offset:15232
	ds_read_b64 v[120:121], v204 offset:17408
	ds_read_b64 v[122:123], v204 offset:19584
	ds_read_b64 v[124:125], v204 offset:21760
	ds_read_b64 v[126:127], v204 offset:23936
	v_pk_fma_f32 v[190:191], v[128:129], v[186:187], v[188:189] op_sel_hi:[0,1,1]
	v_pk_fma_f32 v[186:187], v[128:129], v[186:187], v[188:189] op_sel_hi:[0,1,1] neg_lo:[0,0,1] neg_hi:[0,0,1]
	v_mov_b32_e32 v129, v132
	s_waitcnt lgkmcnt(10)
	v_pk_mul_f32 v[194:195], v[106:107], v[132:133] op_sel_hi:[1,0]
	ds_read_b64 v[134:135], v204 offset:26112
	ds_read_b64 v[176:177], v204 offset:28288
	ds_read_b64 v[178:179], v204 offset:30464
	ds_read_b64 v[180:181], v204 offset:32640
	v_pk_fma_f32 v[196:197], v[106:107], v[128:129], v[194:195] op_sel:[0,0,1] op_sel_hi:[1,1,0] neg_lo:[0,0,1] neg_hi:[0,0,1]
	v_pk_fma_f32 v[106:107], v[106:107], v[128:129], v[194:195] op_sel:[0,0,1] op_sel_hi:[1,0,0]
	v_mov_b32_e32 v188, v190
	v_mov_b32_e32 v197, v107
	v_pk_mul_f32 v[106:107], v[132:133], v[132:133] op_sel:[0,1] op_sel_hi:[0,0]
	v_pk_fma_f32 v[194:195], v[128:129], v[132:133], v[106:107] op_sel_hi:[0,1,1]
	v_pk_fma_f32 v[106:107], v[128:129], v[132:133], v[106:107] op_sel_hi:[0,1,1] neg_lo:[0,0,1] neg_hi:[0,0,1]
	v_mov_b32_e32 v198, v194
	v_mov_b32_e32 v199, v107
	s_waitcnt lgkmcnt(13)
	v_pk_mul_f32 v[194:195], v[108:109], v[194:195] op_sel:[1,0] op_sel_hi:[0,0]
	v_pk_fma_f32 v[200:201], v[108:109], v[106:107], v[194:195] op_sel:[0,1,0] neg_lo:[0,0,1] neg_hi:[0,0,1]
	v_pk_fma_f32 v[106:107], v[108:109], v[106:107], v[194:195] op_sel:[0,1,0]
	v_pk_mul_f32 v[108:109], v[132:133], v[198:199] op_sel:[1,0] op_sel_hi:[0,1]
	v_mov_b32_e32 v201, v107
	v_pk_mul_f32 v[106:107], v[132:133], v[198:199]
	v_pk_add_f32 v[108:109], v[108:109], v[108:109] op_sel:[0,1] op_sel_hi:[0,1]
	s_waitcnt lgkmcnt(12)
	v_pk_mul_f32 v[108:109], v[110:111], v[108:109] op_sel:[1,0] op_sel_hi:[0,1]
	v_pk_add_f32 v[106:107], v[106:107], v[106:107] op_sel:[1,0] op_sel_hi:[1,0] neg_lo:[0,1] neg_hi:[0,1]
	v_mov_b32_e32 v189, v187
	v_pk_fma_f32 v[194:195], v[110:111], v[106:107], v[108:109] neg_lo:[0,0,1] neg_hi:[0,0,1]
	v_pk_fma_f32 v[106:107], v[110:111], v[106:107], v[108:109]
	v_mul_f32_e32 v195, 4.0, v205
	v_sin_f32_e32 v198, v195
	v_cos_f32_e32 v202, v195
	v_mov_b32_e32 v195, v107
	v_pk_mul_f32 v[192:193], v[128:129], v[188:189]
	s_waitcnt lgkmcnt(11)
	v_pk_mul_f32 v[106:107], v[198:199], v[112:113] op_sel:[0,1] op_sel_hi:[0,0]
	v_pk_fma_f32 v[108:109], v[202:203], v[112:113], v[106:107] neg_lo:[0,0,1] neg_hi:[0,0,1]
	v_pk_fma_f32 v[106:107], v[202:203], v[112:113], v[106:107] op_sel_hi:[0,1,1]
	v_mov_b32_e32 v199, v202
	v_mov_b32_e32 v109, v107
	v_pk_mul_f32 v[106:107], v[132:133], v[198:199] op_sel_hi:[0,1]
	v_pk_fma_f32 v[110:111], v[128:129], v[198:199], v[106:107] op_sel:[0,0,1] op_sel_hi:[0,1,0]
	v_pk_fma_f32 v[106:107], v[128:129], v[198:199], v[106:107] op_sel:[0,0,1] op_sel_hi:[0,1,0] neg_lo:[0,0,1] neg_hi:[0,0,1]
	s_waitcnt lgkmcnt(10)
	v_pk_mul_f32 v[198:199], v[110:111], v[114:115] op_sel:[0,1] op_sel_hi:[0,0]
	v_mov_b32_e32 v112, v110
	v_mov_b32_e32 v113, v107
	v_pk_mov_b32 v[110:111], v[106:107], v[110:111] op_sel:[1,0]
	v_pk_fma_f32 v[202:203], v[106:107], v[114:115], v[198:199] op_sel:[1,0,0] neg_lo:[0,0,1] neg_hi:[0,0,1]
	v_pk_fma_f32 v[106:107], v[106:107], v[114:115], v[198:199] op_sel:[1,0,0]
	v_pk_mul_f32 v[188:189], v[132:133], v[188:189]
	v_mov_b32_e32 v203, v107
	v_pk_mul_f32 v[106:107], v[132:133], v[110:111] op_sel_hi:[0,1]
	v_pk_fma_f32 v[110:111], v[128:129], v[112:113], v[106:107] op_sel_hi:[0,1,1]
	v_pk_fma_f32 v[106:107], v[128:129], v[112:113], v[106:107] op_sel_hi:[0,1,1] neg_lo:[0,0,1] neg_hi:[0,0,1]
	v_mov_b32_e32 v112, v110
	v_mov_b32_e32 v113, v107
	s_waitcnt lgkmcnt(9)
	v_pk_mul_f32 v[110:111], v[116:117], v[110:111] op_sel:[1,0] op_sel_hi:[0,0]
	v_pk_fma_f32 v[114:115], v[116:117], v[106:107], v[110:111] op_sel:[0,1,0] neg_lo:[0,0,1] neg_hi:[0,0,1]
	v_pk_fma_f32 v[106:107], v[116:117], v[106:107], v[110:111] op_sel:[0,1,0]
	v_pk_mul_f32 v[110:111], v[128:129], v[112:113]
	v_mov_b32_e32 v115, v107
	v_pk_mul_f32 v[106:107], v[132:133], v[112:113]
	v_pk_add_f32 v[110:111], v[110:111], v[110:111] op_sel:[0,1] op_sel_hi:[0,1]
	s_waitcnt lgkmcnt(8)
	v_pk_mul_f32 v[110:111], v[118:119], v[110:111] op_sel:[1,0] op_sel_hi:[0,1]
	v_pk_add_f32 v[106:107], v[106:107], v[106:107] op_sel:[1,0] op_sel_hi:[1,0] neg_lo:[0,1] neg_hi:[0,1]
	s_nop 0
	v_pk_fma_f32 v[112:113], v[118:119], v[106:107], v[110:111] neg_lo:[0,0,1] neg_hi:[0,0,1]
	v_pk_fma_f32 v[106:107], v[118:119], v[106:107], v[110:111]
	v_mul_f32_e32 v113, 0x41000000, v205
	v_sin_f32_e32 v116, v113
	v_cos_f32_e32 v198, v113
	v_mov_b32_e32 v113, v107
	s_waitcnt lgkmcnt(7)
	v_pk_mul_f32 v[106:107], v[116:117], v[120:121] op_sel:[0,1] op_sel_hi:[0,0]
	v_pk_fma_f32 v[110:111], v[198:199], v[120:121], v[106:107] neg_lo:[0,0,1] neg_hi:[0,0,1]
	v_pk_fma_f32 v[106:107], v[198:199], v[120:121], v[106:107] op_sel_hi:[0,1,1]
	v_mov_b32_e32 v117, v198
	v_mov_b32_e32 v111, v107
	v_pk_mul_f32 v[106:107], v[132:133], v[116:117] op_sel_hi:[0,1]
	v_pk_fma_f32 v[118:119], v[128:129], v[116:117], v[106:107] op_sel:[0,0,1] op_sel_hi:[0,1,0]
	v_pk_fma_f32 v[106:107], v[128:129], v[116:117], v[106:107] op_sel:[0,0,1] op_sel_hi:[0,1,0] neg_lo:[0,0,1] neg_hi:[0,0,1]
	s_waitcnt lgkmcnt(6)
	v_pk_mul_f32 v[120:121], v[118:119], v[122:123] op_sel:[0,1] op_sel_hi:[0,0]
	v_mov_b32_e32 v116, v118
	v_mov_b32_e32 v117, v107
	v_pk_mov_b32 v[118:119], v[106:107], v[118:119] op_sel:[1,0]
	v_pk_fma_f32 v[198:199], v[106:107], v[122:123], v[120:121] op_sel:[1,0,0] neg_lo:[0,0,1] neg_hi:[0,0,1]
	v_pk_fma_f32 v[106:107], v[106:107], v[122:123], v[120:121] op_sel:[1,0,0]
	v_mov_b32_e32 v122, v131
	v_mov_b32_e32 v199, v107
	v_pk_mul_f32 v[106:107], v[132:133], v[118:119] op_sel_hi:[0,1]
	v_pk_fma_f32 v[118:119], v[128:129], v[116:117], v[106:107] op_sel_hi:[0,1,1]
	v_pk_fma_f32 v[106:107], v[128:129], v[116:117], v[106:107] op_sel_hi:[0,1,1] neg_lo:[0,0,1] neg_hi:[0,0,1]
	v_mov_b32_e32 v116, v118
	s_waitcnt lgkmcnt(5)
	v_pk_mul_f32 v[118:119], v[118:119], v[124:125] op_sel:[0,1] op_sel_hi:[0,0]
	v_mov_b32_e32 v117, v107
	v_pk_fma_f32 v[120:121], v[106:107], v[124:125], v[118:119] op_sel:[1,0,0] neg_lo:[0,0,1] neg_hi:[0,0,1]
	v_pk_fma_f32 v[106:107], v[106:107], v[124:125], v[118:119] op_sel:[1,0,0]
	s_nop 0
	v_mov_b32_e32 v121, v107
	v_pk_mul_f32 v[106:107], v[132:133], v[116:117]
	v_pk_mul_f32 v[116:117], v[128:129], v[116:117]
	v_pk_add_f32 v[106:107], v[106:107], v[106:107] op_sel:[1,0] op_sel_hi:[1,0] neg_lo:[0,1] neg_hi:[0,1]
	v_pk_add_f32 v[116:117], v[116:117], v[116:117] op_sel:[0,1] op_sel_hi:[0,1]
	s_waitcnt lgkmcnt(4)
	v_pk_mul_f32 v[116:117], v[116:117], v[126:127] op_sel:[0,1] op_sel_hi:[1,0]
	s_nop 0
	v_pk_fma_f32 v[118:119], v[106:107], v[126:127], v[116:117] neg_lo:[0,0,1] neg_hi:[0,0,1]
	v_pk_fma_f32 v[106:107], v[106:107], v[126:127], v[116:117]
	v_mov_b32_e32 v116, v131
	v_mov_b32_e32 v119, v107
	s_waitcnt lgkmcnt(3)
	v_pk_mul_f32 v[106:107], v[130:131], v[134:135] op_sel:[0,1] op_sel_hi:[0,0]
	v_pk_fma_f32 v[116:117], v[116:117], v[134:135], v[106:107] neg_lo:[0,0,1] neg_hi:[0,0,1]
	v_pk_fma_f32 v[106:107], v[122:123], v[134:135], v[106:107] op_sel_hi:[0,1,1]
	v_mov_b32_e32 v117, v107
	s_waitcnt lgkmcnt(2)
	v_pk_mul_f32 v[106:107], v[184:185], v[176:177] op_sel:[0,1] op_sel_hi:[0,0]
	v_pk_fma_f32 v[122:123], v[182:183], v[176:177], v[106:107] op_sel:[1,0,0] neg_lo:[0,0,1] neg_hi:[0,0,1]
	v_pk_fma_f32 v[106:107], v[182:183], v[176:177], v[106:107] op_sel:[1,0,0]
	v_pk_add_f32 v[126:127], v[192:193], v[192:193] op_sel:[0,1] op_sel_hi:[0,1]
	v_mov_b32_e32 v123, v107
	s_waitcnt lgkmcnt(1)
	v_pk_mul_f32 v[106:107], v[190:191], v[178:179] op_sel:[0,1] op_sel_hi:[0,0]
	v_pk_fma_f32 v[124:125], v[186:187], v[178:179], v[106:107] op_sel:[1,0,0] neg_lo:[0,0,1] neg_hi:[0,0,1]
	v_pk_fma_f32 v[106:107], v[186:187], v[178:179], v[106:107] op_sel:[1,0,0]
	s_waitcnt lgkmcnt(0)
	v_pk_mul_f32 v[126:127], v[126:127], v[180:181] op_sel:[0,1] op_sel_hi:[1,0]
	v_mov_b32_e32 v125, v107
	v_pk_add_f32 v[106:107], v[188:189], v[188:189] op_sel:[1,0] op_sel_hi:[1,0] neg_lo:[0,1] neg_hi:[0,1]
	v_pk_add_f32 v[130:131], v[202:203], v[122:123]
	v_pk_fma_f32 v[128:129], v[106:107], v[180:181], v[126:127] neg_lo:[0,0,1] neg_hi:[0,0,1]
	v_pk_fma_f32 v[106:107], v[106:107], v[180:181], v[126:127]
	v_pk_add_f32 v[122:123], v[202:203], v[122:123] neg_lo:[0,1] neg_hi:[0,1]
	v_mov_b32_e32 v129, v107
	v_pk_add_f32 v[106:107], v[104:105], v[110:111]
	v_pk_add_f32 v[104:105], v[104:105], v[110:111] neg_lo:[0,1] neg_hi:[0,1]
	v_pk_add_f32 v[110:111], v[108:109], v[116:117]
	v_pk_add_f32 v[108:109], v[108:109], v[116:117] neg_lo:[0,1] neg_hi:[0,1]
	v_pk_add_f32 v[126:127], v[196:197], v[198:199] neg_lo:[0,1] neg_hi:[0,1]
	v_xor_b32_e32 v116, 0x80000000, v109
	v_mov_b32_e32 v117, v108
	v_pk_add_f32 v[108:109], v[106:107], v[110:111]
	v_pk_add_f32 v[106:107], v[106:107], v[110:111] neg_lo:[0,1] neg_hi:[0,1]
	v_pk_add_f32 v[110:111], v[104:105], v[116:117]
	v_pk_add_f32 v[104:105], v[104:105], v[116:117] neg_lo:[0,1] neg_hi:[0,1]
	v_pk_add_f32 v[116:117], v[196:197], v[198:199]
	v_xor_b32_e32 v132, 0x80000000, v123
	v_mov_b32_e32 v133, v122
	v_pk_add_f32 v[134:135], v[114:115], v[124:125]
	v_pk_add_f32 v[114:115], v[114:115], v[124:125] neg_lo:[0,1] neg_hi:[0,1]
	v_pk_add_f32 v[122:123], v[116:117], v[130:131]
	v_pk_add_f32 v[116:117], v[116:117], v[130:131] neg_lo:[0,1] neg_hi:[0,1]
	v_pk_add_f32 v[130:131], v[126:127], v[132:133]
	v_pk_add_f32 v[126:127], v[126:127], v[132:133] neg_lo:[0,1] neg_hi:[0,1]
	v_pk_add_f32 v[132:133], v[200:201], v[120:121]
	v_pk_add_f32 v[120:121], v[200:201], v[120:121] neg_lo:[0,1] neg_hi:[0,1]
	v_xor_b32_e32 v124, 0x80000000, v115
	v_mov_b32_e32 v125, v114
	v_pk_add_f32 v[176:177], v[112:113], v[128:129]
	v_pk_add_f32 v[112:113], v[112:113], v[128:129] neg_lo:[0,1] neg_hi:[0,1]
	v_pk_add_f32 v[114:115], v[132:133], v[134:135]
	v_pk_add_f32 v[132:133], v[132:133], v[134:135] neg_lo:[0,1] neg_hi:[0,1]
	v_pk_add_f32 v[134:135], v[120:121], v[124:125]
	v_pk_add_f32 v[120:121], v[120:121], v[124:125] neg_lo:[0,1] neg_hi:[0,1]
	v_pk_add_f32 v[124:125], v[194:195], v[118:119]
	v_pk_add_f32 v[118:119], v[194:195], v[118:119] neg_lo:[0,1] neg_hi:[0,1]
	v_xor_b32_e32 v128, 0x80000000, v113
	v_mov_b32_e32 v129, v112
	v_pk_add_f32 v[112:113], v[124:125], v[176:177]
	v_pk_add_f32 v[124:125], v[124:125], v[176:177] neg_lo:[0,1] neg_hi:[0,1]
	v_pk_add_f32 v[176:177], v[118:119], v[128:129]
	v_pk_add_f32 v[118:119], v[118:119], v[128:129] neg_lo:[0,1] neg_hi:[0,1]
	v_pk_mul_f32 v[128:129], v[130:131], s[30:31] op_sel_hi:[1,0]
	s_nop 0
	v_pk_fma_f32 v[178:179], v[130:131], s[22:23], v[128:129] op_sel:[0,0,1] op_sel_hi:[1,0,0] neg_lo:[0,0,1] neg_hi:[0,0,1]
	v_pk_fma_f32 v[128:129], v[130:131], s[22:23], v[128:129] op_sel:[0,0,1] op_sel_hi:[1,0,0]
	s_nop 0
	v_mov_b32_e32 v179, v129
	v_pk_mul_f32 v[128:129], v[116:117], s[24:25] op_sel_hi:[1,0]
	s_nop 0
	v_pk_fma_f32 v[130:131], v[116:117], s[24:25], v[128:129] op_sel:[0,0,1] op_sel_hi:[1,0,0] neg_lo:[0,0,1] neg_hi:[0,0,1]
	v_pk_fma_f32 v[116:117], v[116:117], s[24:25], v[128:129] op_sel_hi:[1,0,0]
	s_nop 0
	v_mov_b32_e32 v131, v117
	v_pk_mul_f32 v[116:117], v[126:127], s[22:23] op_sel_hi:[1,0]
	s_nop 0
	v_pk_fma_f32 v[128:129], v[126:127], s[30:31], v[116:117] op_sel:[0,0,1] op_sel_hi:[1,0,0] neg_lo:[0,0,1] neg_hi:[0,0,1]
	v_pk_fma_f32 v[116:117], v[126:127], s[30:31], v[116:117] op_sel:[0,0,1] op_sel_hi:[1,0,0]
	s_nop 0
	v_mov_b32_e32 v129, v117
	v_pk_mul_f32 v[116:117], v[134:135], s[24:25] op_sel_hi:[1,0]
	s_nop 0
	v_pk_fma_f32 v[126:127], v[134:135], s[24:25], v[116:117] op_sel:[0,0,1] op_sel_hi:[1,0,0] neg_lo:[0,0,1] neg_hi:[0,0,1]
	v_pk_fma_f32 v[116:117], v[134:135], s[24:25], v[116:117] op_sel_hi:[1,0,0]
	s_nop 0
	v_mov_b32_e32 v127, v117
	v_mov_b32_e32 v117, v132
	v_mul_f32_e32 v132, 0x3f3504f3, v121
	v_xor_b32_e32 v116, 0x80000000, v133
	v_pk_fma_f32 v[120:121], v[120:121], s[18:19], v[132:133] op_sel_hi:[0,1,0] neg_lo:[0,0,1] neg_hi:[0,0,1]
	v_pk_mul_f32 v[132:133], v[176:177], s[22:23] op_sel_hi:[1,0]
	s_nop 0
	v_pk_fma_f32 v[134:135], v[176:177], s[30:31], v[132:133] op_sel:[0,0,1] op_sel_hi:[1,0,0] neg_lo:[0,0,1] neg_hi:[0,0,1]
	v_pk_fma_f32 v[132:133], v[176:177], s[30:31], v[132:133] op_sel:[0,0,1] op_sel_hi:[1,0,0]
	s_nop 0
	v_mul_f32_e32 v132, 0x3f3504f3, v125
	v_mov_b32_e32 v135, v133
	v_pk_fma_f32 v[124:125], v[124:125], s[18:19], v[132:133] op_sel_hi:[0,1,0] neg_lo:[0,0,1] neg_hi:[0,0,1]
	v_pk_mul_f32 v[132:133], v[118:119], s[88:89]
	s_nop 0
	v_pk_fma_f32 v[118:119], v[118:119], s[22:23], v[132:133] op_sel:[0,0,1] op_sel_hi:[1,0,0] neg_lo:[1,0,0] neg_hi:[1,0,0]
	v_pk_add_f32 v[132:133], v[108:109], v[114:115]
	v_pk_add_f32 v[108:109], v[108:109], v[114:115] neg_lo:[0,1] neg_hi:[0,1]
	v_pk_add_f32 v[114:115], v[122:123], v[112:113]
	v_pk_add_f32 v[112:113], v[122:123], v[112:113] neg_lo:[0,1] neg_hi:[0,1]
	s_nop 0
	v_xor_b32_e32 v122, 0x80000000, v113
	v_mov_b32_e32 v123, v112
	v_pk_add_f32 v[112:113], v[132:133], v[114:115]
	v_pk_add_f32 v[114:115], v[132:133], v[114:115] neg_lo:[0,1] neg_hi:[0,1]
	v_pk_add_f32 v[132:133], v[108:109], v[122:123]
	v_pk_add_f32 v[108:109], v[108:109], v[122:123] neg_lo:[0,1] neg_hi:[0,1]
	v_pk_add_f32 v[122:123], v[110:111], v[126:127]
	v_pk_add_f32 v[110:111], v[110:111], v[126:127] neg_lo:[0,1] neg_hi:[0,1]
	v_pk_add_f32 v[126:127], v[178:179], v[134:135]
	v_pk_add_f32 v[134:135], v[178:179], v[134:135] neg_lo:[0,1] neg_hi:[0,1]
	s_nop 0
	v_xor_b32_e32 v176, 0x80000000, v135
	v_mov_b32_e32 v177, v134
	v_pk_add_f32 v[134:135], v[122:123], v[126:127]
	v_pk_add_f32 v[122:123], v[122:123], v[126:127] neg_lo:[0,1] neg_hi:[0,1]
	v_pk_add_f32 v[126:127], v[110:111], v[176:177]
	v_pk_add_f32 v[110:111], v[110:111], v[176:177] neg_lo:[0,1] neg_hi:[0,1]
	v_pk_add_f32 v[176:177], v[106:107], v[116:117]
	v_pk_add_f32 v[106:107], v[106:107], v[116:117] neg_lo:[0,1] neg_hi:[0,1]
	v_pk_add_f32 v[116:117], v[130:131], v[124:125]
	v_pk_add_f32 v[124:125], v[130:131], v[124:125] neg_lo:[0,1] neg_hi:[0,1]
	s_nop 0
	v_xor_b32_e32 v130, 0x80000000, v125
	v_mov_b32_e32 v131, v124
	v_pk_add_f32 v[124:125], v[176:177], v[116:117]
	v_pk_add_f32 v[116:117], v[176:177], v[116:117] neg_lo:[0,1] neg_hi:[0,1]
	v_pk_add_f32 v[176:177], v[106:107], v[130:131]
	v_pk_add_f32 v[106:107], v[106:107], v[130:131] neg_lo:[0,1] neg_hi:[0,1]
	v_pk_add_f32 v[130:131], v[104:105], v[120:121]
	v_pk_add_f32 v[104:105], v[104:105], v[120:121] neg_lo:[0,1] neg_hi:[0,1]
	v_pk_add_f32 v[120:121], v[128:129], v[118:119]
	v_pk_add_f32 v[118:119], v[128:129], v[118:119] neg_lo:[0,1] neg_hi:[0,1]
	s_nop 0
	v_xor_b32_e32 v128, 0x80000000, v119
	v_mov_b32_e32 v129, v118
	v_pk_add_f32 v[118:119], v[130:131], v[120:121]
	v_pk_add_f32 v[120:121], v[130:131], v[120:121] neg_lo:[0,1] neg_hi:[0,1]
	v_pk_add_f32 v[130:131], v[104:105], v[128:129]
	v_pk_add_f32 v[104:105], v[104:105], v[128:129] neg_lo:[0,1] neg_hi:[0,1]
	ds_write_b64 v204, v[112:113]
	ds_write_b64 v204, v[134:135] offset:2176
	ds_write_b64 v204, v[124:125] offset:4352
	ds_write_b64 v204, v[118:119] offset:6528
	ds_write_b64 v204, v[132:133] offset:8704
	ds_write_b64 v204, v[126:127] offset:10880
	ds_write_b64 v204, v[176:177] offset:13056
	ds_write_b64 v204, v[130:131] offset:15232
	ds_write_b64 v204, v[114:115] offset:17408
	ds_write_b64 v204, v[122:123] offset:19584
	ds_write_b64 v204, v[116:117] offset:21760
	ds_write_b64 v204, v[120:121] offset:23936
	ds_write_b64 v204, v[108:109] offset:26112
	ds_write_b64 v204, v[110:111] offset:28288
	ds_write_b64 v204, v[106:107] offset:30464
	ds_write_b64 v204, v[104:105] offset:32640
	s_waitcnt lgkmcnt(0)
	s_barrier
	s_and_saveexec_b64 s[18:19], s[48:49]
	s_cbranch_execz .LBB0_276
	ds_read2_b64 v[110:113], v154 offset1:1
	ds_read_b64 v[106:107], v0
	ds_read_b64 v[114:115], v165 offset:8
	s_waitcnt vmcnt(1)
	v_lshlrev_b32_e32 v105, 16, v2
	v_lshlrev_b32_e32 v104, 16, v162
	v_and_b32_e32 v109, 16, v3
	v_and_b32_e32 v108, 0xffff0000, v2
	s_waitcnt lgkmcnt(0)
	v_mov_b32_e32 v127, v114
	v_mov_b32_e32 v114, v107
	v_mov_b32_e32 v116, v108
	v_pk_mov_b32 v[108:109], v[104:105], v[108:109] op_sel:[1,0]
	v_pk_fma_f32 v[104:105], v[54:55], v[104:105], v[60:61]
	v_mov_b32_e32 v126, v106
	v_pk_mul_f32 v[106:107], v[32:33], v[114:115]
	v_pk_fma_f32 v[104:105], v[56:57], v[108:109], v[104:105]
	v_pk_fma_f32 v[106:107], v[30:31], v[126:127], v[106:107] neg_lo:[0,0,1] neg_hi:[0,0,1]
	v_mov_b32_e32 v108, v110
	v_mov_b32_e32 v109, v112
	ds_read_b64 v[118:119], v166 offset:16
	ds_read_b64 v[124:125], v167 offset:24
	v_pk_add_f32 v[108:109], v[108:109], v[106:107]
	s_waitcnt vmcnt(0)
	v_lshlrev_b32_e32 v107, 16, v24
	v_lshlrev_b32_e32 v106, 16, v164
	v_and_b32_e32 v129, 16, v25
	v_and_b32_e32 v128, 0xffff0000, v24
	v_mov_b32_e32 v130, v128
	v_pk_mov_b32 v[128:129], v[106:107], v[128:129] op_sel:[1,0]
	v_pk_fma_f32 v[106:107], v[54:55], v[106:107], v[60:61]
	v_pk_mul_f32 v[126:127], v[32:33], v[126:127]
	ds_read2_b64 v[120:123], v154 offset0:2 offset1:3
	v_pk_fma_f32 v[106:107], v[56:57], v[128:129], v[106:107]
	v_pk_fma_f32 v[114:115], v[30:31], v[114:115], v[126:127]
	ds_read2_b64 v[126:129], v154 offset0:4 offset1:5
	ds_read_b64 v[132:133], v168 offset:32
	ds_read_b64 v[134:135], v169 offset:40
	v_mov_b32_e32 v112, v111
	v_pk_add_f32 v[110:111], v[112:113], v[114:115]
	v_and_b32_e32 v114, 0xffff0000, v3
	v_lshlrev_b32_e32 v177, 16, v4
	v_mov_b32_e32 v176, v114
	v_and_b32_e32 v113, 16, v5
	v_and_b32_e32 v112, 0xffff0000, v4
	s_waitcnt lgkmcnt(4)
	v_mov_b32_e32 v185, v124
	v_mov_b32_e32 v124, v119
	v_mov_b32_e32 v180, v112
	v_pk_mov_b32 v[178:179], v[176:177], v[112:113] op_sel:[1,0]
	v_mov_b32_e32 v184, v118
	v_pk_mul_f32 v[112:113], v[62:63], v[124:125]
	s_waitcnt lgkmcnt(3)
	v_mov_b32_e32 v118, v120
	v_pk_fma_f32 v[112:113], v[34:35], v[184:185], v[112:113] neg_lo:[0,0,1] neg_hi:[0,0,1]
	v_mov_b32_e32 v119, v122
	s_waitcnt lgkmcnt(0)
	v_mov_b32_e32 v189, v134
	v_mov_b32_e32 v134, v133
	v_lshlrev_b32_e32 v117, 16, v3
	v_and_b32_e32 v115, 16, v4
	v_pk_add_f32 v[112:113], v[118:119], v[112:113]
	v_mov_b32_e32 v188, v132
	v_pk_mul_f32 v[118:119], v[66:67], v[134:135]
	v_pk_fma_f32 v[182:183], v[54:55], v[116:117], v[60:61]
	v_pk_mov_b32 v[114:115], v[116:117], v[114:115] op_sel:[1,0]
	v_pk_fma_f32 v[118:119], v[64:65], v[188:189], v[118:119] neg_lo:[0,0,1] neg_hi:[0,0,1]
	v_mov_b32_e32 v132, v126
	v_mov_b32_e32 v133, v128
	v_pk_mul_f32 v[184:185], v[62:63], v[184:185]
	v_lshlrev_b32_e32 v131, 16, v25
	v_pk_fma_f32 v[114:115], v[56:57], v[114:115], v[182:183]
	ds_read_b64 v[182:183], v174 offset:48
	ds_read_b64 v[186:187], v175 offset:56
	v_pk_add_f32 v[118:119], v[132:133], v[118:119]
	v_and_b32_e32 v133, 16, v26
	v_and_b32_e32 v132, 0xffff0000, v25
	v_pk_fma_f32 v[124:125], v[34:35], v[124:125], v[184:185]
	v_mov_b32_e32 v122, v121
	v_pk_fma_f32 v[104:105], v[58:59], v[116:117], v[104:105]
	v_pk_fma_f32 v[106:107], v[58:59], v[130:131], v[106:107]
	v_pk_fma_f32 v[116:117], v[58:59], v[176:177], v[114:115]
	v_pk_fma_f32 v[114:115], v[54:55], v[176:177], v[60:61]
	v_pk_fma_f32 v[196:197], v[54:55], v[130:131], v[60:61]
	v_pk_add_f32 v[120:121], v[122:123], v[124:125]
	v_pk_mov_b32 v[122:123], v[130:131], v[132:133] op_sel:[1,0]
	v_pk_mul_f32 v[130:131], v[66:67], v[188:189]
	v_pk_fma_f32 v[114:115], v[56:57], v[178:179], v[114:115]
	ds_read2_b64 v[176:179], v154 offset0:6 offset1:7
	v_pk_fma_f32 v[130:131], v[64:65], v[134:135], v[130:131]
	v_mov_b32_e32 v128, v127
	v_lshlrev_b32_e32 v181, 16, v5
	v_pk_add_f32 v[126:127], v[128:129], v[130:131]
	v_and_b32_e32 v129, 16, v161
	v_and_b32_e32 v128, 0xffff0000, v5
	v_mov_b32_e32 v190, v132
	v_mov_b32_e32 v130, v128
	v_pk_mov_b32 v[128:129], v[180:181], v[128:129] op_sel:[1,0]
	v_pk_fma_f32 v[132:133], v[54:55], v[180:181], v[60:61]
	v_lshlrev_b32_e32 v131, 16, v161
	v_pk_fma_f32 v[128:129], v[56:57], v[128:129], v[132:133]
	s_waitcnt lgkmcnt(1)
	v_mov_b32_e32 v135, v186
	v_mov_b32_e32 v186, v183
	v_pk_fma_f32 v[128:129], v[58:59], v[130:131], v[128:129]
	v_mov_b32_e32 v134, v182
	v_pk_mul_f32 v[130:131], v[70:71], v[186:187]
	v_and_b32_e32 v192, 0xffff0000, v26
	v_pk_fma_f32 v[130:131], v[68:69], v[134:135], v[130:131] neg_lo:[0,0,1] neg_hi:[0,0,1]
	s_waitcnt lgkmcnt(0)
	v_mov_b32_e32 v132, v176
	v_mov_b32_e32 v133, v178
	v_lshlrev_b32_e32 v191, 16, v26
	v_and_b32_e32 v193, 16, v27
	v_lshlrev_b32_e32 v195, 16, v27
	v_mov_b32_e32 v194, v192
	v_pk_fma_f32 v[122:123], v[56:57], v[122:123], v[196:197]
	v_pk_add_f32 v[132:133], v[132:133], v[130:131]
	v_and_b32_e32 v131, 16, v163
	v_and_b32_e32 v130, 0xffff0000, v27
	v_pk_fma_f32 v[114:115], v[58:59], v[180:181], v[114:115]
	v_pk_mov_b32 v[192:193], v[190:191], v[192:193] op_sel:[1,0]
	v_pk_fma_f32 v[124:125], v[58:59], v[190:191], v[122:123]
	v_pk_fma_f32 v[122:123], v[54:55], v[190:191], v[60:61]
	v_mov_b32_e32 v180, v130
	v_pk_mov_b32 v[130:131], v[194:195], v[130:131] op_sel:[1,0]
	v_pk_fma_f32 v[182:183], v[54:55], v[194:195], v[60:61]
	v_pk_mul_f32 v[134:135], v[70:71], v[134:135]
	v_pk_fma_f32 v[122:123], v[56:57], v[192:193], v[122:123]
	v_lshlrev_b32_e32 v181, 16, v163
	v_pk_fma_f32 v[130:131], v[56:57], v[130:131], v[182:183]
	v_pk_fma_f32 v[134:135], v[68:69], v[186:187], v[134:135]
	v_mov_b32_e32 v178, v177
	v_pk_fma_f32 v[122:123], v[58:59], v[194:195], v[122:123]
	v_pk_fma_f32 v[130:131], v[58:59], v[180:181], v[130:131]
	v_pk_add_f32 v[134:135], v[178:179], v[134:135]
	s_andn2_b64 vcc, exec, s[8:9]
	s_mov_b64 s[88:89], -1
	s_cbranch_vccnz .LBB0_302
	s_mov_b64 s[88:89], 0
	v_fma_f32 v108, v6, v8, v108
	v_fma_f32 v109, v6, v9, v109
	v_fma_f32 v112, v6, v10, v112
	v_fma_f32 v113, v6, v11, v113
	v_fma_f32 v118, v6, v12, v118
	v_fma_f32 v119, v6, v13, v119
	v_fma_f32 v132, v6, v14, v132
	v_fma_f32 v133, v6, v15, v133
	v_fma_f32 v110, v6, v16, v110
	v_fma_f32 v111, v6, v17, v111
	v_fma_f32 v120, v6, v18, v120
	v_fma_f32 v121, v6, v19, v121
	v_fma_f32 v126, v6, v20, v126
	v_fma_f32 v127, v6, v21, v127
	v_fma_f32 v134, v6, v22, v134
	v_fma_f32 v135, v6, v23, v135
	v_mul_f32_e32 v108, v104, v108
	v_mul_f32_e32 v109, v105, v109
	v_mul_f32_e32 v112, v116, v112
	v_mul_f32_e32 v113, v117, v113
	v_mul_f32_e32 v118, v114, v118
	v_mul_f32_e32 v119, v115, v119
	v_mul_f32_e32 v132, v128, v132
	v_mul_f32_e32 v133, v129, v133
	v_mul_f32_e32 v110, v106, v110
	v_mul_f32_e32 v111, v107, v111
	v_mul_f32_e32 v120, v124, v120
	v_mul_f32_e32 v121, v125, v121
	v_mul_f32_e32 v126, v122, v126
	v_mul_f32_e32 v127, v123, v127
	v_mul_f32_e32 v134, v130, v134
	v_mul_f32_e32 v135, v131, v135
	v_cvt_pk_bf16_f32 v8, v108, v109
	v_cvt_pk_bf16_f32 v9, v112, v113
	v_cvt_pk_bf16_f32 v10, v118, v119
	v_cvt_pk_bf16_f32 v11, v132, v133
	v_cvt_pk_bf16_f32 v12, v110, v111
	v_cvt_pk_bf16_f32 v13, v120, v121
	v_cvt_pk_bf16_f32 v14, v126, v127
	v_cvt_pk_bf16_f32 v15, v134, v135
	s_mul_i32 s36, s2, 0x11000
	s_add_u32 s36, s36, 0x6d00000
	s_add_u32 s36, s64, s36
	s_addc_u32 s37, s65, 0
	v_add_u32_e32 v176, s14, v44
	v_lshlrev_b32_e32 v176, 1, v176
	v_add_u32_e32 v177, 0x2000, v176
	global_store_dwordx4 v176, v[8:11], s[36:37]
	global_store_dwordx4 v177, v[12:15], s[36:37]

.LBB0_304:
	s_mov_b64 exec, -1
	v_readlane_b32 s6, v255, 29
	s_load_dwordx4 s[48:51], s[0:1], 0x50
	s_load_dwordx2 s[52:53], s[0:1], 0x98
	s_nop 3
	s_mul_i32 s7, s2, 0x4400
	s_lshl_b32 s8, s7, 1
	s_add_u32 s10, s64, 0x8f00000
	s_addc_u32 s11, s65, 0
	s_add_u32 s10, s10, s8
	s_addc_u32 s11, s11, 0
	s_add_u32 s10, s10, 0x8000
	s_addc_u32 s11, s11, 0
	s_add_u32 s12, s64, 0x11c00000
	s_addc_u32 s13, s65, 0
	s_add_u32 s12, s12, s7
	s_addc_u32 s13, s13, 0
	s_add_u32 s12, s12, 0x4000
	s_addc_u32 s13, s13, 0
	s_mul_i32 s8, s2, 0x11000
	s_add_u32 s8, s8, 0x6d08000
	s_add_u32 s16, s64, s8
	s_addc_u32 s17, s65, 0
	v_and_b32_e32 v8, 0xff, v208
	v_lshrrev_b32_e32 v9, 8, v208
	v_and_b32_e32 v10, 31, v208
	v_bfe_u32 v11, v208, 5, 1
	v_lshrrev_b32_e32 v0, 6, v208
	s_nop 0
	v_readfirstlane_b32 s14, v0
	v_lshlrev_b32_e32 v2, 2, v8
	global_load_dword v14, v2, s[12:13]
	v_add_u32_e32 v3, 0x880000, v2
	global_load_dword v15, v3, s[12:13]
	v_add_u32_e32 v3, 0x1100000, v2
	global_load_dword v16, v3, s[12:13]
	v_add_u32_e32 v3, 0x1980000, v2
	global_load_dword v17, v3, s[12:13]
	v_lshlrev_b32_e32 v2, 1, v208
	global_load_ushort v18, v2, s[10:11] offset:-2
	global_load_ushort v19, v2, s[10:11]
	global_load_ushort v20, v2, s[10:11] offset:2
	global_load_ushort v21, v2, s[10:11] offset:1022
	global_load_ushort v22, v2, s[10:11] offset:1024
	global_load_ushort v23, v2, s[10:11] offset:1026
	v_lshlrev_b32_e32 v3, 10, v9
	v_lshl_add_u32 v3, v8, 1, v3
	v_add_u32_e32 v4, 0x1100000, v3
	global_load_ushort v24, v4, s[10:11] offset:-2
	global_load_ushort v25, v4, s[10:11]
	global_load_ushort v26, v4, s[10:11] offset:2
	global_load_ushort v27, v4, s[10:11] offset:510
	global_load_ushort v28, v4, s[10:11] offset:512
	global_load_ushort v29, v4, s[10:11] offset:514
	v_add_u32_e32 v4, 0x2200000, v3
	global_load_ushort v30, v4, s[10:11] offset:-2
	global_load_ushort v31, v4, s[10:11]
	global_load_ushort v32, v4, s[10:11] offset:2
	global_load_ushort v33, v4, s[10:11] offset:510
	global_load_ushort v34, v4, s[10:11] offset:512
	global_load_ushort v35, v4, s[10:11] offset:514
	s_waitcnt lgkmcnt(0)
	s_mul_i32 s8, s6, 0x4800
	s_lshl_b32 s9, s2, 2
	s_add_u32 s48, s48, s8
	s_addc_u32 s49, s49, 0
	s_add_u32 s48, s48, s9
	s_addc_u32 s49, s49, 0
	s_mul_i32 s8, s6, 0x1800
	s_add_u32 s50, s50, s8
	s_addc_u32 s51, s51, 0
	s_add_u32 s50, s50, s9
	s_addc_u32 s51, s51, 0
	s_lshl_b32 s8, s6, 12
	s_add_u32 s52, s52, s8
	s_addc_u32 s53, s53, 0
	s_add_u32 s52, s52, s9
	s_addc_u32 s53, s53, 0
	global_load_dword v36, v1, s[48:49]
	v_mov_b32_e32 v4, 0x1800
	global_load_dword v37, v4, s[48:49]
	v_mov_b32_e32 v4, 0x3000
	global_load_dword v38, v4, s[48:49]
	global_load_dword v39, v1, s[50:51]
	global_load_dword v40, v1, s[48:49] offset:2048
	v_mov_b32_e32 v4, 0x2000
	global_load_dword v41, v4, s[48:49]
	v_mov_b32_e32 v4, 0x3800
	global_load_dword v42, v4, s[48:49]
	global_load_dword v43, v1, s[50:51] offset:2048
	global_load_dword v44, v1, s[52:53]
	v_mov_b32_e32 v4, 0x1000
	global_load_dword v45, v4, s[48:49]
	v_mov_b32_e32 v4, 0x2800
	global_load_dword v46, v4, s[48:49]
	v_mov_b32_e32 v4, 0x4000
	global_load_dword v47, v4, s[48:49]
	v_mov_b32_e32 v4, 0x1000
	global_load_dword v48, v4, s[50:51]
	global_load_dword v49, v1, s[52:53] offset:2048
	v_mov_b32_e32 v4, 0
	v_mov_b32_e32 v5, 0
	v_mov_b32_e32 v6, 0
	v_mov_b32_e32 v7, 0
	v_mul_u32_u24_e32 v0, 48, v208
	v_add_u32_e32 v0, 0x1000, v0
	ds_write_b128 v0, v[4:7]
	ds_write_b128 v0, v[4:7] offset:16
	ds_write_b128 v0, v[4:7] offset:32
	v_sub_u32_e32 v56, v10, v11
	v_lshlrev_b32_e32 v56, 2, v56
	v_add_u32_e32 v56, 900, v56
	v_lshrrev_b32_e32 v2, 3, v10
	v_mul_u32_u24_e32 v2, 744, v2
	v_and_b32_e32 v3, 7, v10
	v_mad_u32_u24 v2, v3, 33, v2
	v_add_u32_e32 v2, v2, v11
	v_lshlrev_b32_e32 v57, 2, v2
	v_add_u32_e32 v57, 924, v57
	v_mul_u32_u24_e32 v2, 33, v10
	v_lshl_add_u32 v2, v11, 2, v2
	v_lshlrev_b32_e32 v58, 2, v2
	s_mul_i32 s8, s14, 4224
	s_add_i32 s8, s8, 0x8000
	v_add_u32_e32 v58, s8, v58
	v_lshrrev_b32_e32 v2, 5, v8
	v_lshl_add_u32 v2, v9, 4, v2
	v_mul_u32_u24_e32 v2, 33, v2
	v_and_b32_e32 v3, 31, v8
	v_add_u32_e32 v2, v2, v3
	v_lshlrev_b32_e32 v59, 2, v2
	v_add_u32_e32 v59, 0x8000, v59
	v_lshrrev_b32_e32 v2, 5, v8
	v_add_u32_e32 v2, 7, v2
	v_mul_u32_u24_e32 v2, 33, v2
	v_add_u32_e32 v2, v2, v3
	v_mul_u32_u24_e32 v4, 1488, v9
	v_add_u32_e32 v2, v2, v4
	v_lshlrev_b32_e32 v60, 2, v2
	v_mul_u32_u24_e32 v4, 744, v9
	v_sub_u32_e32 v2, v2, v4
	v_lshlrev_b32_e32 v61, 2, v2
	v_cvt_f32_i32_e32 v2, s2
	v_mov_b32_e32 v3, 0xc0447cbd
	v_fmamk_f32 v12, v2, 0xbcc4df2d, v3
	v_and_b32_e32 v0, 0x7fffffff, v12
	s_mov_b32 s46, 0x437f0000
	v_div_scale_f32 v2, s[8:9], s46, s46, v0
	v_rcp_f32_e32 v3, v2
	v_div_scale_f32 v0, vcc, v0, s46, v0
	v_fma_f32 v4, -v2, v3, 1.0
	v_fmac_f32_e32 v3, v4, v3
	v_mul_f32_e32 v4, v0, v3
	v_fma_f32 v5, -v2, v4, v0
	v_fmac_f32_e32 v4, v5, v3
	v_fma_f32 v0, -v2, v4, v0
	v_div_fmas_f32 v0, v0, v3, v4
	v_div_fixup_f32 v0, v0, s46, |v12|
	v_cvt_f32_i32_e32 v2, v8
	v_mul_f32_e32 v0, v0, v2
	v_mul_f32_e32 v0, 0xbfb8aa3b, v0
	v_exp_f32_e32 v13, v0
	v_cmp_ne_u32_e64 s[54:55], 0, v8
	s_movk_i32 s9, 0xff
	v_cmp_ne_u32_e64 s[46:47], s9, v8
	s_waitcnt vmcnt(0)
	v_mul_f32_e32 v14, v14, v13
	v_mul_f32_e32 v15, v15, v13
	v_mul_f32_e32 v16, v16, v13
	v_mul_f32_e32 v17, v17, v13
	v_cndmask_b32_e64 v15, 0, v15, s[54:55]
	v_cndmask_b32_e64 v17, 0, v17, s[54:55]
	v_lshlrev_b32_e32 v2, 2, v8
	v_add_u32_e32 v3, 1020, v2
	v_sub_u32_e32 v4, 1020, v2
	v_mov_b32_e32 v5, 0x7fc
	v_cndmask_b32_e64 v4, v5, v4, s[54:55]
	v_cmp_gt_u32_e32 vcc, 0x100, v208
	s_and_saveexec_b64 s[8:9], vcc
	ds_write_b32 v3, v14 offset:0
	ds_write_b32 v4, v15 offset:0
	ds_write_b32 v3, v16 offset:2048
	ds_write_b32 v4, v17 offset:2048
	s_mov_b64 exec, s[8:9]
	v_mul_f32_e32 v54, v14, v14
	v_fmac_f32_e32 v54, v15, v15
	v_mul_f32_e32 v55, v16, v16
	v_fmac_f32_e32 v55, v17, v17
	v_cndmask_b32_e32 v54, 0, v54, vcc
	v_cndmask_b32_e32 v55, 0, v55, vcc
	v_lshlrev_b32_e32 v18, 16, v18
	v_lshlrev_b32_e32 v19, 16, v19
	v_lshlrev_b32_e32 v20, 16, v20
	v_cndmask_b32_e64 v18, 0, v18, s[54:55]
	v_cndmask_b32_e64 v20, 0, v20, s[46:47]
	v_fma_f32 v62, v37, v19, v39
	v_fmac_f32_e32 v62, v36, v18
	v_fmac_f32_e32 v62, v38, v20
	v_lshlrev_b32_e32 v21, 16, v21
	v_lshlrev_b32_e32 v22, 16, v22
	v_lshlrev_b32_e32 v23, 16, v23
	v_cndmask_b32_e64 v21, 0, v21, s[54:55]
	v_cndmask_b32_e64 v23, 0, v23, s[46:47]
	v_fma_f32 v63, v37, v22, v39
	v_fmac_f32_e32 v63, v36, v21
	v_fmac_f32_e32 v63, v38, v23
	v_lshlrev_b32_e32 v24, 16, v24
	v_lshlrev_b32_e32 v25, 16, v25
	v_lshlrev_b32_e32 v26, 16, v26
	v_cndmask_b32_e64 v24, 0, v24, s[54:55]
	v_cndmask_b32_e64 v26, 0, v26, s[46:47]
	v_fma_f32 v50, v41, v25, v43
	v_fmac_f32_e32 v50, v40, v24
	v_fmac_f32_e32 v50, v42, v26
	v_lshlrev_b32_e32 v27, 16, v27
	v_lshlrev_b32_e32 v28, 16, v28
	v_lshlrev_b32_e32 v29, 16, v29
	v_cndmask_b32_e64 v27, 0, v27, s[54:55]
	v_cndmask_b32_e64 v29, 0, v29, s[46:47]
	v_fma_f32 v51, v41, v28, v43
	v_fmac_f32_e32 v51, v40, v27
	v_fmac_f32_e32 v51, v42, v29
	v_lshlrev_b32_e32 v30, 16, v30
	v_lshlrev_b32_e32 v31, 16, v31
	v_lshlrev_b32_e32 v32, 16, v32
	v_cndmask_b32_e64 v30, 0, v30, s[54:55]
	v_cndmask_b32_e64 v32, 0, v32, s[46:47]
	v_fma_f32 v52, v46, v31, v48
	v_fmac_f32_e32 v52, v45, v30
	v_fmac_f32_e32 v52, v47, v32
	v_lshlrev_b32_e32 v33, 16, v33
	v_lshlrev_b32_e32 v34, 16, v34
	v_lshlrev_b32_e32 v35, 16, v35
	v_cndmask_b32_e64 v33, 0, v33, s[54:55]
	v_cndmask_b32_e64 v35, 0, v35, s[46:47]
	v_fma_f32 v53, v46, v34, v48
	v_fmac_f32_e32 v53, v45, v33
	v_fmac_f32_e32 v53, v47, v35
	ds_swizzle_b32 v2, v54 offset:0x41f
	ds_swizzle_b32 v3, v55 offset:0x41f
	s_waitcnt lgkmcnt(0)
	v_add_f32_e32 v54, v54, v2
	v_add_f32_e32 v55, v55, v3
	ds_swizzle_b32 v2, v54 offset:0x81f
	ds_swizzle_b32 v3, v55 offset:0x81f
	s_waitcnt lgkmcnt(0)
	v_add_f32_e32 v54, v54, v2
	v_add_f32_e32 v55, v55, v3
	ds_swizzle_b32 v2, v54 offset:0x101f
	ds_swizzle_b32 v3, v55 offset:0x101f
	s_waitcnt lgkmcnt(0)
	v_add_f32_e32 v54, v54, v2
	v_add_f32_e32 v55, v55, v3
	ds_swizzle_b32 v2, v54 offset:0x201f
	ds_swizzle_b32 v3, v55 offset:0x201f
	s_waitcnt lgkmcnt(0)
	v_add_f32_e32 v54, v54, v2
	v_add_f32_e32 v55, v55, v3
	ds_swizzle_b32 v2, v54 offset:0x401f
	ds_swizzle_b32 v3, v55 offset:0x401f
	s_waitcnt lgkmcnt(0)
	v_add_f32_e32 v54, v54, v2
	v_add_f32_e32 v55, v55, v3
	s_nop 1
	v_readlane_b32 s8, v54, 0
	v_readlane_b32 s9, v54, 32
	v_readlane_b32 s46, v55, 0
	v_readlane_b32 s47, v55, 32
	s_nop 3
	v_mov_b32_e32 v2, s8
	v_add_f32_e32 v2, s9, v2
	v_mov_b32_e32 v3, s46
	v_add_f32_e32 v3, s47, v3
	s_lshl_b32 s8, s14, 2
	s_add_i32 s8, s8, 0x10800
	v_mov_b32_e32 v4, s8
	ds_write_b32 v4, v2
	ds_write_b32 v4, v3 offset:32
	s_waitcnt lgkmcnt(0)
	s_barrier
	ds_write_b32 v61, v62 offset:4096
	ds_write_b32 v61, v63 offset:10048
	s_waitcnt lgkmcnt(0)
	s_barrier
	v_mov_b32_e32 v2, 0x10800
	ds_read_b128 v[4:7], v2
	ds_read_b128 v[18:21], v2 offset:16
	ds_read_b128 v[22:25], v2 offset:32
	ds_read_b128 v[26:29], v2 offset:48
	s_waitcnt lgkmcnt(0)
	v_add_f32_e32 v0, 0, v4
	v_add_f32_e32 v0, v0, v5
	v_add_f32_e32 v0, v0, v6
	v_add_f32_e32 v0, v0, v7
	v_add_f32_e32 v0, v0, v18
	v_add_f32_e32 v0, v0, v19
	v_add_f32_e32 v0, v0, v20
	v_add_f32_e32 v0, v0, v21
	v_add_f32_e32 v0, 0x358637bd, v0
	v_mul_f32_e32 v2, 0x4f800000, v0
	v_cmp_gt_f32_e32 vcc, s23, v0
	s_nop 1
	v_cndmask_b32_e32 v0, v0, v2, vcc
	v_sqrt_f32_e32 v2, v0
	s_nop 0
	v_add_u32_e32 v3, -1, v2
	v_fma_f32 v31, -v3, v2, v0
	v_add_u32_e32 v30, 1, v2
	v_cmp_ge_f32_e64 s[8:9], 0, v31
	s_nop 1
	v_cndmask_b32_e64 v3, v2, v3, s[8:9]
	v_fma_f32 v2, -v30, v2, v0
	v_cmp_lt_f32_e64 s[8:9], 0, v2
	s_nop 1
	v_cndmask_b32_e64 v2, v3, v30, s[8:9]
	v_mul_f32_e32 v3, 0x37800000, v2
	v_cndmask_b32_e32 v2, v2, v3, vcc
	v_cmp_class_f32_e32 vcc, v0, v210
	s_nop 1
	v_cndmask_b32_e32 v0, v2, v0, vcc
	v_div_scale_f32 v30, s[8:9], v0, v0, 1.0
	v_rcp_f32_e32 v31, v30
	v_div_scale_f32 v32, vcc, 1.0, v0, 1.0
	v_fma_f32 v2, -v30, v31, 1.0
	v_fmac_f32_e32 v31, v2, v31
	v_mul_f32_e32 v33, v32, v31
	v_fma_f32 v2, -v30, v33, v32
	v_fmac_f32_e32 v33, v2, v31
	v_fma_f32 v30, -v30, v33, v32
	v_div_fmas_f32 v30, v30, v31, v33
	v_div_fixup_f32 v54, v30, v0, 1.0
	v_add_f32_e32 v0, 0, v22
	v_add_f32_e32 v0, v0, v23
	v_add_f32_e32 v0, v0, v24
	v_add_f32_e32 v0, v0, v25
	v_add_f32_e32 v0, v0, v26
	v_add_f32_e32 v0, v0, v27
	v_add_f32_e32 v0, v0, v28
	v_add_f32_e32 v0, v0, v29
	v_add_f32_e32 v0, 0x358637bd, v0
	v_mul_f32_e32 v2, 0x4f800000, v0
	v_cmp_gt_f32_e32 vcc, s23, v0
	s_nop 1
	v_cndmask_b32_e32 v0, v0, v2, vcc
	v_sqrt_f32_e32 v2, v0
	s_nop 0
	v_add_u32_e32 v3, -1, v2
	v_fma_f32 v31, -v3, v2, v0
	v_add_u32_e32 v30, 1, v2
	v_cmp_ge_f32_e64 s[8:9], 0, v31
	s_nop 1
	v_cndmask_b32_e64 v3, v2, v3, s[8:9]
	v_fma_f32 v2, -v30, v2, v0
	v_cmp_lt_f32_e64 s[8:9], 0, v2
	s_nop 1
	v_cndmask_b32_e64 v2, v3, v30, s[8:9]
	v_mul_f32_e32 v3, 0x37800000, v2
	v_cndmask_b32_e32 v2, v2, v3, vcc
	v_cmp_class_f32_e32 vcc, v0, v210
	s_nop 1
	v_cndmask_b32_e32 v0, v2, v0, vcc
	v_div_scale_f32 v30, s[8:9], v0, v0, 1.0
	v_rcp_f32_e32 v31, v30
	v_div_scale_f32 v32, vcc, 1.0, v0, 1.0
	v_fma_f32 v2, -v30, v31, 1.0
	v_fmac_f32_e32 v31, v2, v31
	v_mul_f32_e32 v33, v32, v31
	v_fma_f32 v2, -v30, v33, v32
	v_fmac_f32_e32 v33, v2, v31
	v_fma_f32 v30, -v30, v33, v32
	v_div_fmas_f32 v30, v30, v31, v33
	v_div_fixup_f32 v55, v30, v0, 1.0
	s_lshl_b32 s8, s14, 8
	s_add_i32 s8, s8, -896
	s_mul_i32 s9, s14, -264
	s_add_i32 s9, s9, 924
	v_add_u32_e32 v2, s8, v56
	v_add_u32_e32 v3, s9, v57
	ds_read_b32 v80, v2 offset:120
	ds_read_b32 v96, v3 offset:4096
	ds_read_b32 v81, v2 offset:112
	ds_read_b32 v97, v3 offset:4104
	ds_read_b32 v82, v2 offset:104
	ds_read_b32 v98, v3 offset:4112
	ds_read_b32 v83, v2 offset:96
	ds_read_b32 v99, v3 offset:4120
	ds_read_b32 v84, v2 offset:88
	ds_read_b32 v100, v3 offset:4128
	ds_read_b32 v85, v2 offset:80
	ds_read_b32 v101, v3 offset:4136
	ds_read_b32 v86, v2 offset:72
	ds_read_b32 v102, v3 offset:4144
	ds_read_b32 v87, v2 offset:64
	ds_read_b32 v103, v3 offset:4152
	ds_read_b32 v88, v2 offset:56
	ds_read_b32 v104, v3 offset:4160
	ds_read_b32 v89, v2 offset:48
	ds_read_b32 v105, v3 offset:4168
	ds_read_b32 v90, v2 offset:40
	ds_read_b32 v106, v3 offset:4176
	ds_read_b32 v91, v2 offset:32
	ds_read_b32 v107, v3 offset:4184
	ds_read_b32 v92, v2 offset:24
	ds_read_b32 v108, v3 offset:4192
	ds_read_b32 v93, v2 offset:16
	ds_read_b32 v109, v3 offset:4200
	ds_read_b32 v94, v2 offset:8
	ds_read_b32 v110, v3 offset:4208
	ds_read_b32 v95, v2 offset:0
	ds_read_b32 v111, v3 offset:4216
	s_cmp_eq_u32 s14, 7
	s_cbranch_scc1 .Lhc_o0_skipq2
	v_add_u32_e32 v2, 0x80, v2
	v_add_u32_e32 v3, 0xffffff7c, v3
	ds_read_b32 v112, v2 offset:120
	ds_read_b32 v128, v3 offset:4096
	ds_read_b32 v113, v2 offset:112
	ds_read_b32 v129, v3 offset:4104
	ds_read_b32 v114, v2 offset:104
	ds_read_b32 v130, v3 offset:4112
	ds_read_b32 v115, v2 offset:96
	ds_read_b32 v131, v3 offset:4120
	ds_read_b32 v116, v2 offset:88
	ds_read_b32 v132, v3 offset:4128
	ds_read_b32 v117, v2 offset:80
	ds_read_b32 v133, v3 offset:4136
	ds_read_b32 v118, v2 offset:72
	ds_read_b32 v134, v3 offset:4144
	ds_read_b32 v119, v2 offset:64
	ds_read_b32 v135, v3 offset:4152
	ds_read_b32 v120, v2 offset:56
	ds_read_b32 v136, v3 offset:4160
	ds_read_b32 v121, v2 offset:48
	ds_read_b32 v137, v3 offset:4168
	ds_read_b32 v122, v2 offset:40
	ds_read_b32 v138, v3 offset:4176
	ds_read_b32 v123, v2 offset:32
	ds_read_b32 v139, v3 offset:4184
	ds_read_b32 v124, v2 offset:24
	ds_read_b32 v140, v3 offset:4192
	ds_read_b32 v125, v2 offset:16
	ds_read_b32 v141, v3 offset:4200
	ds_read_b32 v126, v2 offset:8
	ds_read_b32 v142, v3 offset:4208
	ds_read_b32 v127, v2 offset:0
	ds_read_b32 v143, v3 offset:4216

.Lhc_o1_q2done:
	s_nop 15
	s_nop 3
	ds_write_b32 v58, v64 offset:0
	ds_write_b32 v58, v65 offset:4
	ds_write_b32 v58, v66 offset:8
	ds_write_b32 v58, v67 offset:12
	ds_write_b32 v58, v68 offset:32
	ds_write_b32 v58, v69 offset:36
	ds_write_b32 v58, v70 offset:40
	ds_write_b32 v58, v71 offset:44
	ds_write_b32 v58, v72 offset:64
	ds_write_b32 v58, v73 offset:68
	ds_write_b32 v58, v74 offset:72
	ds_write_b32 v58, v75 offset:76
	ds_write_b32 v58, v76 offset:96
	ds_write_b32 v58, v77 offset:100
	ds_write_b32 v58, v78 offset:104
	ds_write_b32 v58, v79 offset:108
	s_waitcnt lgkmcnt(0)
	s_barrier
	ds_read_b32 v144, v59 offset:0
	ds_read_b32 v152, v59 offset:1056
	ds_read_b32 v145, v59 offset:4224
	ds_read_b32 v153, v59 offset:5280
	ds_read_b32 v146, v59 offset:8448
	ds_read_b32 v154, v59 offset:9504
	ds_read_b32 v147, v59 offset:12672
	ds_read_b32 v155, v59 offset:13728
	ds_read_b32 v148, v59 offset:16896
	ds_read_b32 v156, v59 offset:17952
	ds_read_b32 v149, v59 offset:21120
	ds_read_b32 v157, v59 offset:22176
	ds_read_b32 v150, v59 offset:25344
	ds_read_b32 v158, v59 offset:26400
	ds_read_b32 v151, v59 offset:29568
	ds_read_b32 v159, v59 offset:30624
	s_waitcnt lgkmcnt(0)
	v_add_f32_e32 v144, v144, v145
	v_add_f32_e32 v152, v152, v153
	v_add_f32_e32 v144, v144, v146
	v_add_f32_e32 v152, v152, v154
	v_add_f32_e32 v144, v144, v147
	v_add_f32_e32 v152, v152, v155
	v_add_f32_e32 v144, v144, v148
	v_add_f32_e32 v152, v152, v156
	v_add_f32_e32 v144, v144, v149
	v_add_f32_e32 v152, v152, v157
	v_add_f32_e32 v144, v144, v150
	v_add_f32_e32 v152, v152, v158
	v_add_f32_e32 v144, v144, v151
	v_add_f32_e32 v152, v152, v159
	v_mul_f32_e32 v2, v49, v62
	v_mul_f32_e32 v3, v49, v63
	v_fmac_f32_e32 v2, v55, v144
	v_fmac_f32_e32 v3, v55, v152
	v_mul_f32_e32 v2, v52, v2
	v_mul_f32_e32 v3, v53, v3
	v_lshl_add_u32 v4, v9, 9, v8
	v_lshlrev_b32_e32 v4, 1, v4
	v_bfe_u32 v5, v2, 16, 1
	v_add3_u32 v5, v2, v5, s90
	global_store_short_d16_hi v4, v5, s[16:17]
	v_bfe_u32 v5, v3, 16, 1
	v_add3_u32 v5, v3, v5, s90
	global_store_short_d16_hi v4, v5, s[16:17] offset:512
	s_mov_b32 s34, 0xc200000
	s_waitcnt lgkmcnt(0)
	s_barrier
	s_branch .LBB0_244

.Ltr_phase:
	s_load_dwordx2 s[64:65], s[72:73], 0x120
	v_and_b32_e32 v2, 7, v208
	v_bfe_u32 v3, v208, 3, 3
	v_lshrrev_b32_e32 v0, 6, v208
	s_nop 0
	v_readfirstlane_b32 s84, v0
	v_mul_u32_u24_e32 v4, 0x11000, v3
	v_lshl_add_u32 v4, v2, 4, v4
	v_lshlrev_b32_e32 v5, 11, v3
	v_lshl_add_u32 v5, v2, 4, v5
	s_mul_i32 s38, s84, 8448
	v_mul_u32_u24_e32 v6, 1056, v2
	v_lshl_add_u32 v6, v3, 1, v6
	v_add_u32_e32 v6, s38, v6
	v_mul_u32_u24_e32 v7, 132, v3
	v_lshl_add_u32 v7, v2, 4, v7
	v_add_u32_e32 v7, s38, v7
	s_mul_i32 s98, s84, 0x440000
	s_lshl_b32 s99, s84, 7
	s_mov_b32 s38, s96
	s_waitcnt lgkmcnt(0)
.Ltr_loop:
	s_cmpk_ge_u32 s38, 0x110
	s_cbranch_scc1 .Ltr_done
	s_lshl_b32 s100, s38, 7
	s_add_u32 s100, s100, s98
	s_add_u32 s100, s100, 0x6d00000
	s_add_u32 s2, s64, s100
	s_addc_u32 s3, s65, 0
	s_lshl_b32 s100, s38, 17
	s_add_u32 s100, s100, s99
	s_add_u32 s100, s100, 0xed00000
	s_add_u32 s6, s64, s100
	s_addc_u32 s7, s65, 0
	v_mov_b32_e32 v8, v4
	global_load_dwordx4 v[16:19], v8, s[2:3]
	v_add_u32_e32 v8, 0x88000, v8
	global_load_dwordx4 v[20:23], v8, s[2:3]
	v_add_u32_e32 v8, 0x88000, v8
	global_load_dwordx4 v[24:27], v8, s[2:3]
	v_add_u32_e32 v8, 0x88000, v8
	global_load_dwordx4 v[28:31], v8, s[2:3]
	v_add_u32_e32 v8, 0x88000, v8
	global_load_dwordx4 v[32:35], v8, s[2:3]
	v_add_u32_e32 v8, 0x88000, v8
	global_load_dwordx4 v[36:39], v8, s[2:3]
	v_add_u32_e32 v8, 0x88000, v8
	global_load_dwordx4 v[40:43], v8, s[2:3]
	v_add_u32_e32 v8, 0x88000, v8
	global_load_dwordx4 v[44:47], v8, s[2:3]
	s_waitcnt vmcnt(7)
	ds_write_b16 v6, v16 offset:0
	ds_write_b16_d16_hi v6, v16 offset:132
	ds_write_b16 v6, v17 offset:264
	ds_write_b16_d16_hi v6, v17 offset:396
	ds_write_b16 v6, v18 offset:528
	ds_write_b16_d16_hi v6, v18 offset:660
	ds_write_b16 v6, v19 offset:792
	ds_write_b16_d16_hi v6, v19 offset:924
	s_waitcnt vmcnt(6)
	ds_write_b16 v6, v20 offset:16
	ds_write_b16_d16_hi v6, v20 offset:148
	ds_write_b16 v6, v21 offset:280
	ds_write_b16_d16_hi v6, v21 offset:412
	ds_write_b16 v6, v22 offset:544
	ds_write_b16_d16_hi v6, v22 offset:676
	ds_write_b16 v6, v23 offset:808
	ds_write_b16_d16_hi v6, v23 offset:940
	s_waitcnt vmcnt(5)
	ds_write_b16 v6, v24 offset:32
	ds_write_b16_d16_hi v6, v24 offset:164
	ds_write_b16 v6, v25 offset:296
	ds_write_b16_d16_hi v6, v25 offset:428
	ds_write_b16 v6, v26 offset:560
	ds_write_b16_d16_hi v6, v26 offset:692
	ds_write_b16 v6, v27 offset:824
	ds_write_b16_d16_hi v6, v27 offset:956
	s_waitcnt vmcnt(4)
	ds_write_b16 v6, v28 offset:48
	ds_write_b16_d16_hi v6, v28 offset:180
	ds_write_b16 v6, v29 offset:312
	ds_write_b16_d16_hi v6, v29 offset:444
	ds_write_b16 v6, v30 offset:576
	ds_write_b16_d16_hi v6, v30 offset:708
	ds_write_b16 v6, v31 offset:840
	ds_write_b16_d16_hi v6, v31 offset:972
	s_waitcnt vmcnt(3)
	ds_write_b16 v6, v32 offset:64
	ds_write_b16_d16_hi v6, v32 offset:196
	ds_write_b16 v6, v33 offset:328
	ds_write_b16_d16_hi v6, v33 offset:460
	ds_write_b16 v6, v34 offset:592
	ds_write_b16_d16_hi v6, v34 offset:724
	ds_write_b16 v6, v35 offset:856
	ds_write_b16_d16_hi v6, v35 offset:988
	s_waitcnt vmcnt(2)
	ds_write_b16 v6, v36 offset:80
	ds_write_b16_d16_hi v6, v36 offset:212
	ds_write_b16 v6, v37 offset:344
	ds_write_b16_d16_hi v6, v37 offset:476
	ds_write_b16 v6, v38 offset:608
	ds_write_b16_d16_hi v6, v38 offset:740
	ds_write_b16 v6, v39 offset:872
	ds_write_b16_d16_hi v6, v39 offset:1004
	s_waitcnt vmcnt(1)
	ds_write_b16 v6, v40 offset:96
	ds_write_b16_d16_hi v6, v40 offset:228
	ds_write_b16 v6, v41 offset:360
	ds_write_b16_d16_hi v6, v41 offset:492
	ds_write_b16 v6, v42 offset:624
	ds_write_b16_d16_hi v6, v42 offset:756
	ds_write_b16 v6, v43 offset:888
	ds_write_b16_d16_hi v6, v43 offset:1020
	s_waitcnt vmcnt(0)
	ds_write_b16 v6, v44 offset:112
	ds_write_b16_d16_hi v6, v44 offset:244
	ds_write_b16 v6, v45 offset:376
	ds_write_b16_d16_hi v6, v45 offset:508
	ds_write_b16 v6, v46 offset:640
	ds_write_b16_d16_hi v6, v46 offset:772
	ds_write_b16 v6, v47 offset:904
	ds_write_b16_d16_hi v6, v47 offset:1036
	ds_read_b32 v48, v7 offset:0
	ds_read_b32 v49, v7 offset:4
	ds_read_b32 v50, v7 offset:8
	ds_read_b32 v51, v7 offset:12
	ds_read_b32 v52, v7 offset:1056
	ds_read_b32 v53, v7 offset:1060
	ds_read_b32 v54, v7 offset:1064
	ds_read_b32 v55, v7 offset:1068
	ds_read_b32 v56, v7 offset:2112
	ds_read_b32 v57, v7 offset:2116
	ds_read_b32 v58, v7 offset:2120
	ds_read_b32 v59, v7 offset:2124
	ds_read_b32 v60, v7 offset:3168
	ds_read_b32 v61, v7 offset:3172
	ds_read_b32 v62, v7 offset:3176
	ds_read_b32 v63, v7 offset:3180
	ds_read_b32 v64, v7 offset:4224
	ds_read_b32 v65, v7 offset:4228
	ds_read_b32 v66, v7 offset:4232
	ds_read_b32 v67, v7 offset:4236
	ds_read_b32 v68, v7 offset:5280
	ds_read_b32 v69, v7 offset:5284
	ds_read_b32 v70, v7 offset:5288
	ds_read_b32 v71, v7 offset:5292
	ds_read_b32 v72, v7 offset:6336
	ds_read_b32 v73, v7 offset:6340
	ds_read_b32 v74, v7 offset:6344
	ds_read_b32 v75, v7 offset:6348
	ds_read_b32 v76, v7 offset:7392
	ds_read_b32 v77, v7 offset:7396
	ds_read_b32 v78, v7 offset:7400
	ds_read_b32 v79, v7 offset:7404
	v_mov_b32_e32 v8, v5
	s_waitcnt lgkmcnt(0)
	global_store_dwordx4 v8, v[48:51], s[6:7]
	v_add_u32_e32 v8, 0x4000, v8
	global_store_dwordx4 v8, v[52:55], s[6:7]
	v_add_u32_e32 v8, 0x4000, v8
	global_store_dwordx4 v8, v[56:59], s[6:7]
	v_add_u32_e32 v8, 0x4000, v8
	global_store_dwordx4 v8, v[60:63], s[6:7]
	v_add_u32_e32 v8, 0x4000, v8
	global_store_dwordx4 v8, v[64:67], s[6:7]
	v_add_u32_e32 v8, 0x4000, v8
	global_store_dwordx4 v8, v[68:71], s[6:7]
	v_add_u32_e32 v8, 0x4000, v8
	global_store_dwordx4 v8, v[72:75], s[6:7]
	v_add_u32_e32 v8, 0x4000, v8
	global_store_dwordx4 v8, v[76:79], s[6:7]
	s_add_i32 s38, s38, s56
	s_waitcnt lgkmcnt(0)
	s_branch .Ltr_loop
.Ltr_done:
	s_mov_b64 s[0:1], s[72:73]
	s_branch .LBB0_568

	.amdhsa_kernel _Z6mk_fwd4Args
		.amdhsa_group_segment_fixed_size 0
		.amdhsa_private_segment_fixed_size 0
		.amdhsa_kernarg_size 560
		.amdhsa_user_sgpr_count 2
		.amdhsa_user_sgpr_dispatch_ptr 0
		.amdhsa_user_sgpr_queue_ptr 0
		.amdhsa_user_sgpr_kernarg_segment_ptr 1
		.amdhsa_user_sgpr_dispatch_id 0
		.amdhsa_user_sgpr_kernarg_preload_length 0
		.amdhsa_user_sgpr_kernarg_preload_offset 0
		.amdhsa_user_sgpr_private_segment_size 0
		.amdhsa_uses_dynamic_stack 0
		.amdhsa_enable_private_segment 0
		.amdhsa_system_sgpr_workgroup_id_x 1
		.amdhsa_system_sgpr_workgroup_id_y 0
		.amdhsa_system_sgpr_workgroup_id_z 0
		.amdhsa_system_sgpr_workgroup_info 0
		.amdhsa_system_vgpr_workitem_id 2
		.amdhsa_next_free_vgpr 256
		.amdhsa_next_free_sgpr 102
		.amdhsa_accum_offset 256
		.amdhsa_reserve_vcc 1
		.amdhsa_float_round_mode_32 0
		.amdhsa_float_round_mode_16_64 0
		.amdhsa_float_denorm_mode_32 3
		.amdhsa_float_denorm_mode_16_64 3
		.amdhsa_dx10_clamp 1
		.amdhsa_ieee_mode 1
		.amdhsa_fp16_overflow 0
		.amdhsa_tg_split 0
		.amdhsa_exception_fp_ieee_invalid_op 0
		.amdhsa_exception_fp_denorm_src 0
		.amdhsa_exception_fp_ieee_div_zero 0
		.amdhsa_exception_fp_ieee_overflow 0
		.amdhsa_exception_fp_ieee_underflow 0
		.amdhsa_exception_fp_ieee_inexact 0
		.amdhsa_exception_int_div_zero 0
	.end_amdhsa_kernel

amdhsa.kernels:
  - .agpr_count:     0
    .args:
      - .offset:         0
        .size:           304
        .value_kind:     by_value
      - .offset:         304
        .size:           4
        .value_kind:     hidden_block_count_x
      - .offset:         308
        .size:           4
        .value_kind:     hidden_block_count_y
      - .offset:         312
        .size:           4
        .value_kind:     hidden_block_count_z
      - .offset:         316
        .size:           2
        .value_kind:     hidden_group_size_x
      - .offset:         318
        .size:           2
        .value_kind:     hidden_group_size_y
      - .offset:         320
        .size:           2
        .value_kind:     hidden_group_size_z
      - .offset:         322
        .size:           2
        .value_kind:     hidden_remainder_x
      - .offset:         324
        .size:           2
        .value_kind:     hidden_remainder_y
      - .offset:         326
        .size:           2
        .value_kind:     hidden_remainder_z
      - .offset:         344
        .size:           8
        .value_kind:     hidden_global_offset_x
      - .offset:         352
        .size:           8
        .value_kind:     hidden_global_offset_y
      - .offset:         360
        .size:           8
        .value_kind:     hidden_global_offset_z
      - .offset:         368
        .size:           2
        .value_kind:     hidden_grid_dims
      - .offset:         392
        .size:           8
        .value_kind:     hidden_multigrid_sync_arg
      - .offset:         424
        .size:           4
        .value_kind:     hidden_dynamic_lds_size
    .group_segment_fixed_size: 0
    .kernarg_segment_align: 8
    .kernarg_segment_size: 560
    .language:       OpenCL C
    .language_version:
      - 2
      - 0
    .max_flat_workgroup_size: 512
    .name:           _Z6mk_fwd4Args
    .private_segment_fixed_size: 0
    .sgpr_count:     108
    .sgpr_spill_count: 182
    .symbol:         _Z6mk_fwd4Args.kd
    .uniform_work_group_size: 1
    .uses_dynamic_stack: false
    .vgpr_count:     256
    .vgpr_spill_count: 0
    .wavefront_size: 64
